# resid-epilogue loads issued up front (hand-written), unit-tail store drain removed, layer-0 conversion tail rebalanced
# speedup vs baseline: 1.0062x; 1.0062x over previous
.LBB0_481:
	ds_read_b128 v[110:113], v236
	ds_read_b128 v[114:117], v236 offset:64
	ds_read_b128 v[118:121], v236 offset:2560
	ds_read_b128 v[122:125], v236 offset:2624
	ds_read_b128 v[126:129], v236 offset:5120
	ds_read_b128 v[142:145], v236 offset:5184
	ds_read_b128 v[130:133], v236 offset:7680
	ds_read_b128 v[146:149], v236 offset:7744
	s_add_i32 s90, s64, 2
	s_min_i32 s6, s90, s87
	s_cmp_ge_i32 s6, s84
	s_mov_b64 s[12:13], -1
	s_cbranch_scc0 .LBB0_487
	s_cmp_ge_i32 s6, s85
	s_mov_b64 s[10:11], -1
	s_cbranch_scc0 .LBB0_484
	s_sub_i32 s52, s6, s85
	s_mov_b64 s[10:11], 0
	s_mov_b64 s[8:9], s[52:53]

.LBB0_489:
	s_lshl_b64 s[6:7], s[8:9], 14
	s_add_u32 s6, s10, s6
	s_addc_u32 s7, s11, s7
	s_cmp_eq_u64 s[12:13], 0
	v_lshl_add_u64 v[98:99], s[12:13], 0, v[204:205]
	v_lshl_add_u64 v[106:107], s[6:7], 0, v[204:205]
	s_cselect_b64 s[6:7], -1, 0
	v_cndmask_b32_e64 v99, v99, v107, s[6:7]
	v_cndmask_b32_e64 v98, v98, v106, s[6:7]
	global_load_dwordx4 v[98:101], v[98:99], off
	global_load_dwordx4 v[102:105], v[106:107], off
	v_lshl_add_u64 v[106:107], v[106:107], 0, s[54:55]
	global_load_dwordx4 v[106:109], v[106:107], off
	s_setprio 1
	s_waitcnt lgkmcnt(7)
	v_mfma_f32_16x16x32_bf16 v[134:137], v[110:113], v[58:61], 0
	v_mfma_f32_16x16x32_bf16 v[110:113], v[110:113], v[66:69], 0
	s_waitcnt lgkmcnt(5)
	v_mfma_f32_16x16x32_bf16 v[150:153], v[118:121], v[58:61], 0
	v_mfma_f32_16x16x32_bf16 v[210:213], v[118:121], v[66:69], 0
	s_waitcnt lgkmcnt(3)
	v_mfma_f32_16x16x32_bf16 v[214:217], v[126:129], v[58:61], 0
	v_mfma_f32_16x16x32_bf16 v[126:129], v[126:129], v[66:69], 0
	s_waitcnt lgkmcnt(1)
	v_mfma_f32_16x16x32_bf16 v[218:221], v[130:133], v[58:61], 0
	v_mfma_f32_16x16x32_bf16 v[222:225], v[130:133], v[66:69], 0
	v_mfma_f32_16x16x32_bf16 v[138:141], v[114:117], v[62:65], v[134:137]
	v_mfma_f32_16x16x32_bf16 v[110:113], v[114:117], v[70:73], v[110:113]
	v_mfma_f32_16x16x32_bf16 v[118:121], v[122:125], v[62:65], v[150:153]
	v_mfma_f32_16x16x32_bf16 v[130:133], v[122:125], v[70:73], v[210:213]
	v_mfma_f32_16x16x32_bf16 v[134:137], v[142:145], v[62:65], v[214:217]
	v_mfma_f32_16x16x32_bf16 v[122:125], v[142:145], v[70:73], v[126:129]
	s_waitcnt lgkmcnt(0)
	v_mfma_f32_16x16x32_bf16 v[126:129], v[146:149], v[62:65], v[218:221]
	v_mfma_f32_16x16x32_bf16 v[114:117], v[146:149], v[70:73], v[222:225]
	s_setprio 0
	s_cmp_lt_u32 s64, s84
	s_mov_b64 s[8:9], -1
	s_cbranch_scc1 .LBB0_491
	s_cmp_lt_u32 s64, s85
	s_cselect_b64 vcc, -1, 0
	v_cndmask_b32_e32 v142, v239, v240, vcc
	v_cvt_f32_i32_e32 v142, v142
	v_cndmask_b32_e32 v144, v242, v241, vcc
	v_cvt_f32_i32_e32 v144, v144
	v_cndmask_b32_e32 v143, v232, v231, vcc
	v_mul_f32_e32 v142, v143, v142
	v_exp_f32_e32 v206, v142
	v_mul_f32_e32 v142, v143, v144
	v_exp_f32_e32 v208, v142
	s_mov_b64 s[8:9], 0
	v_pk_mul_f32 v[152:153], v[206:207], v[140:141] op_sel_hi:[0,1]
	v_pk_mul_f32 v[150:151], v[206:207], v[138:139] op_sel_hi:[0,1]
	v_pk_mul_f32 v[144:145], v[206:207], v[136:137] op_sel_hi:[0,1]
	v_pk_mul_f32 v[142:143], v[206:207], v[134:135] op_sel_hi:[0,1]
	v_pk_mul_f32 v[148:149], v[208:209], v[132:133] op_sel_hi:[0,1]
	v_pk_mul_f32 v[146:147], v[208:209], v[130:131] op_sel_hi:[0,1]
	v_mul_f32_e32 v245, v208, v116
	v_pk_mul_f32 v[218:219], v[208:209], v[114:115] op_sel_hi:[0,1]

.LBB0_564:
	v_pk_mul_f32 v[128:129], v[214:215], v[128:129]
	v_pk_mul_f32 v[126:127], v[212:213], v[126:127]
	v_pk_mul_f32 v[214:215], v[222:223], v[122:123]
	v_pk_mul_f32 v[114:115], v[210:211], v[120:121]
	v_pk_mul_f32 v[118:119], v[206:207], v[118:119]
	v_pk_mul_f32 v[120:121], v[220:221], v[112:113]
	v_pk_mul_f32 v[122:123], v[216:217], v[110:111]
	v_mul_f32_e32 v206, v117, v208
	v_add_u32_e32 v207, 0x5000, v237
	v_add_u32_e32 v208, 0x5800, v237
	v_add_u32_e32 v216, 0x6000, v237
	v_add_u32_e32 v217, 0x6800, v237
	v_add_u32_e32 v220, 0x7000, v237
	v_add_u32_e32 v221, 0x7800, v237
	v_add_u32_e32 v222, 0x8800, v237
	v_add_u32_e32 v223, 0x9000, v237
	v_pk_mul_f32 v[212:213], v[224:225], v[124:125]
	v_cvt_pk_bf16_f32 v110, v150, v151
	v_cvt_pk_bf16_f32 v111, v152, v153
	v_cvt_pk_bf16_f32 v112, v118, v119
	v_cvt_pk_bf16_f32 v113, v114, v115
	v_cvt_pk_bf16_f32 v114, v122, v123
	v_cvt_pk_bf16_f32 v115, v120, v121
	v_cvt_pk_bf16_f32 v116, v146, v147
	v_cvt_pk_bf16_f32 v117, v148, v149
	v_cvt_pk_bf16_f32 v118, v142, v143
	v_cvt_pk_bf16_f32 v119, v144, v145
	v_cvt_pk_bf16_f32 v120, v126, v127
	v_cvt_pk_bf16_f32 v121, v128, v129
	ds_read2_b64 v[122:125], v207 offset1:4
	ds_read2_b64 v[126:129], v208 offset0:48 offset1:52
	ds_read2_b64 v[130:133], v216 offset0:96 offset1:100
	ds_read2_b64 v[134:137], v217 offset0:144 offset1:148
	ds_read2_b64 v[138:141], v220 offset0:192 offset1:196
	ds_read2_b64 v[142:145], v221 offset0:240 offset1:244
	ds_read2_b64 v[146:149], v222 offset0:32 offset1:36
	ds_read2_b64 v[150:153], v223 offset0:80 offset1:84
	v_cvt_pk_bf16_f32 v210, v214, v215
	v_cvt_pk_bf16_f32 v211, v212, v213
	v_cvt_pk_bf16_f32 v212, v218, v219
	v_cvt_pk_bf16_f32 v213, v245, v206
	s_setprio 1
	s_waitcnt lgkmcnt(7)
	v_mfma_f32_16x16x32_bf16 v[54:57], v[122:125], v[110:113], v[54:57]
	v_mfma_f32_16x16x32_bf16 v[22:25], v[122:125], v[114:117], v[22:25]
	s_waitcnt lgkmcnt(6)
	v_mfma_f32_16x16x32_bf16 v[50:53], v[126:129], v[110:113], v[50:53]
	v_mfma_f32_16x16x32_bf16 v[18:21], v[126:129], v[114:117], v[18:21]
	s_waitcnt lgkmcnt(5)
	v_mfma_f32_16x16x32_bf16 v[46:49], v[130:133], v[110:113], v[46:49]
	v_mfma_f32_16x16x32_bf16 v[14:17], v[130:133], v[114:117], v[14:17]
	s_waitcnt lgkmcnt(4)
	v_mfma_f32_16x16x32_bf16 v[42:45], v[134:137], v[110:113], v[42:45]
	v_mfma_f32_16x16x32_bf16 v[10:13], v[134:137], v[114:117], v[10:13]
	s_setprio 0
	ds_read2_b64 v[122:125], v207 offset0:8 offset1:12
	ds_read2_b64 v[126:129], v208 offset0:56 offset1:60
	ds_read2_b64 v[130:133], v216 offset0:104 offset1:108
	ds_read2_b64 v[134:137], v217 offset0:152 offset1:156
	s_setprio 1
	s_waitcnt lgkmcnt(7)
	v_mfma_f32_16x16x32_bf16 v[38:41], v[138:141], v[110:113], v[38:41]
	v_mfma_f32_16x16x32_bf16 v[6:9], v[138:141], v[114:117], v[6:9]
	s_waitcnt lgkmcnt(6)
	v_mfma_f32_16x16x32_bf16 v[34:37], v[142:145], v[110:113], v[34:37]
	v_mfma_f32_16x16x32_bf16 v[2:5], v[142:145], v[114:117], v[2:5]
	s_waitcnt lgkmcnt(5)
	v_mfma_f32_16x16x32_bf16 v[78:81], v[146:149], v[110:113], v[78:81]
	v_mfma_f32_16x16x32_bf16 v[30:33], v[146:149], v[114:117], v[30:33]
	s_waitcnt lgkmcnt(4)
	v_mfma_f32_16x16x32_bf16 v[74:77], v[150:153], v[110:113], v[74:77]
	v_mfma_f32_16x16x32_bf16 v[26:29], v[150:153], v[114:117], v[26:29]
	s_setprio 0
	ds_read2_b64 v[110:113], v220 offset0:200 offset1:204
	ds_read2_b64 v[114:117], v221 offset0:248 offset1:252
	ds_read2_b64 v[138:141], v222 offset0:40 offset1:44
	ds_read2_b64 v[142:145], v223 offset0:88 offset1:92
	s_setprio 1
	s_waitcnt lgkmcnt(7)
	v_mfma_f32_16x16x32_bf16 v[54:57], v[122:125], v[118:121], v[54:57]
	v_mfma_f32_16x16x32_bf16 v[22:25], v[122:125], v[210:213], v[22:25]
	s_waitcnt lgkmcnt(6)
	v_mfma_f32_16x16x32_bf16 v[50:53], v[126:129], v[118:121], v[50:53]
	v_mfma_f32_16x16x32_bf16 v[18:21], v[126:129], v[210:213], v[18:21]
	s_waitcnt lgkmcnt(5)
	v_mfma_f32_16x16x32_bf16 v[46:49], v[130:133], v[118:121], v[46:49]
	v_mfma_f32_16x16x32_bf16 v[14:17], v[130:133], v[210:213], v[14:17]
	s_waitcnt lgkmcnt(4)
	v_mfma_f32_16x16x32_bf16 v[42:45], v[134:137], v[118:121], v[42:45]
	v_mfma_f32_16x16x32_bf16 v[10:13], v[134:137], v[210:213], v[10:13]
	s_setprio 0
	s_setprio 1
	s_waitcnt lgkmcnt(3)
	v_mfma_f32_16x16x32_bf16 v[38:41], v[110:113], v[118:121], v[38:41]
	v_mfma_f32_16x16x32_bf16 v[6:9], v[110:113], v[210:213], v[6:9]
	s_waitcnt lgkmcnt(2)
	v_mfma_f32_16x16x32_bf16 v[34:37], v[114:117], v[118:121], v[34:37]
	v_mfma_f32_16x16x32_bf16 v[2:5], v[114:117], v[210:213], v[2:5]
	s_waitcnt lgkmcnt(1)
	v_mfma_f32_16x16x32_bf16 v[78:81], v[138:141], v[118:121], v[78:81]
	v_mfma_f32_16x16x32_bf16 v[30:33], v[138:141], v[210:213], v[30:33]
	s_waitcnt lgkmcnt(0)
	v_mfma_f32_16x16x32_bf16 v[74:77], v[142:145], v[118:121], v[74:77]
	v_mfma_f32_16x16x32_bf16 v[26:29], v[142:145], v[210:213], v[26:29]
	s_setprio 0
	v_cmp_eq_u32_e32 vcc, 0, v244
	s_waitcnt vmcnt(3)
	s_or_b32 s16, s64, 1
	s_cmp_ge_u32 s16, s86
	v_cndmask_b32_e32 v113, v83, v87, vcc
	v_cndmask_b32_e32 v112, v92, v86, vcc
	v_cndmask_b32_e32 v111, v1, v85, vcc
	v_cndmask_b32_e32 v110, v82, v84, vcc
	ds_write_b128 v169, v[110:113] offset:10240
	v_add_u32_e32 v110, 0x9c00, v171
	ds_write2_b64 v110, v[88:89], v[90:91] offset1:1
	v_add_u32_e32 v110, 0xc200, v171
	ds_write2_b64 v110, v[94:95], v[96:97] offset1:1
	s_waitcnt lgkmcnt(0)
	s_barrier
	s_cbranch_scc1 .LBB0_649
	ds_read_b128 v[110:113], v236 offset:10240
	ds_read_b128 v[114:117], v236 offset:10304
	ds_read_b128 v[118:121], v236 offset:12800
	ds_read_b128 v[122:125], v236 offset:12864
	ds_read_b128 v[126:129], v236 offset:15360
	ds_read_b128 v[142:145], v236 offset:15424
	ds_read_b128 v[130:133], v236 offset:17920
	ds_read_b128 v[146:149], v236 offset:17984
	s_add_i32 s8, s64, 3
	s_min_i32 s8, s8, s87
	s_cmp_ge_i32 s8, s84
	s_mov_b64 s[14:15], -1
	s_cbranch_scc0 .LBB0_571
	s_cmp_ge_i32 s8, s85
	s_mov_b64 s[12:13], -1
	s_cbranch_scc0 .LBB0_568
	s_sub_i32 s52, s8, s85
	s_mov_b64 s[12:13], 0
	s_mov_b64 s[10:11], s[52:53]

.LBB0_573:
	s_lshl_b64 s[8:9], s[10:11], 14
	s_add_u32 s8, s12, s8
	s_addc_u32 s9, s13, s9
	s_cmp_eq_u64 s[14:15], 0
	v_lshl_add_u64 v[84:85], s[14:15], 0, v[204:205]
	v_lshl_add_u64 v[94:95], s[8:9], 0, v[204:205]
	s_cselect_b64 s[8:9], -1, 0
	v_cndmask_b32_e64 v85, v85, v95, s[8:9]
	v_cndmask_b32_e64 v84, v84, v94, s[8:9]
	global_load_dwordx4 v[84:87], v[84:85], off
	global_load_dwordx4 v[88:91], v[94:95], off
	v_lshl_add_u64 v[94:95], v[94:95], 0, s[54:55]
	global_load_dwordx4 v[94:97], v[94:95], off
	s_setprio 1
	s_waitcnt lgkmcnt(7)
	v_mfma_f32_16x16x32_bf16 v[134:137], v[110:113], v[58:61], 0
	v_mfma_f32_16x16x32_bf16 v[110:113], v[110:113], v[66:69], 0
	s_waitcnt lgkmcnt(5)
	v_mfma_f32_16x16x32_bf16 v[150:153], v[118:121], v[58:61], 0
	v_mfma_f32_16x16x32_bf16 v[210:213], v[118:121], v[66:69], 0
	s_waitcnt lgkmcnt(3)
	v_mfma_f32_16x16x32_bf16 v[214:217], v[126:129], v[58:61], 0
	v_mfma_f32_16x16x32_bf16 v[126:129], v[126:129], v[66:69], 0
	s_waitcnt lgkmcnt(1)
	v_mfma_f32_16x16x32_bf16 v[218:221], v[130:133], v[58:61], 0
	v_mfma_f32_16x16x32_bf16 v[222:225], v[130:133], v[66:69], 0
	v_mfma_f32_16x16x32_bf16 v[138:141], v[114:117], v[62:65], v[134:137]
	v_mfma_f32_16x16x32_bf16 v[110:113], v[114:117], v[70:73], v[110:113]
	v_mfma_f32_16x16x32_bf16 v[118:121], v[122:125], v[62:65], v[150:153]
	v_mfma_f32_16x16x32_bf16 v[130:133], v[122:125], v[70:73], v[210:213]
	v_mfma_f32_16x16x32_bf16 v[134:137], v[142:145], v[62:65], v[214:217]
	v_mfma_f32_16x16x32_bf16 v[122:125], v[142:145], v[70:73], v[126:129]
	s_waitcnt lgkmcnt(0)
	v_mfma_f32_16x16x32_bf16 v[126:129], v[146:149], v[62:65], v[218:221]
	v_mfma_f32_16x16x32_bf16 v[114:117], v[146:149], v[70:73], v[222:225]
	s_setprio 0
	s_cmp_lt_u32 s16, s84
	s_mov_b64 s[10:11], -1
	s_cbranch_scc1 .LBB0_575
	s_cmp_lt_u32 s16, s85
	s_cselect_b64 vcc, -1, 0
	v_cndmask_b32_e32 v142, v239, v240, vcc
	v_cvt_f32_i32_e32 v142, v142
	v_cndmask_b32_e32 v144, v242, v241, vcc
	v_cvt_f32_i32_e32 v144, v144
	v_cndmask_b32_e32 v143, v232, v231, vcc
	v_mul_f32_e32 v142, v143, v142
	v_exp_f32_e32 v206, v142
	v_mul_f32_e32 v142, v143, v144
	v_exp_f32_e32 v208, v142
	s_mov_b64 s[10:11], 0
	v_pk_mul_f32 v[152:153], v[206:207], v[140:141] op_sel_hi:[0,1]
	v_pk_mul_f32 v[150:151], v[206:207], v[138:139] op_sel_hi:[0,1]
	v_pk_mul_f32 v[144:145], v[206:207], v[136:137] op_sel_hi:[0,1]
	v_pk_mul_f32 v[142:143], v[206:207], v[134:135] op_sel_hi:[0,1]
	v_pk_mul_f32 v[148:149], v[208:209], v[132:133] op_sel_hi:[0,1]
	v_pk_mul_f32 v[146:147], v[208:209], v[130:131] op_sel_hi:[0,1]
	v_mul_f32_e32 v245, v208, v116
	v_pk_mul_f32 v[218:219], v[208:209], v[114:115] op_sel_hi:[0,1]

.LBB0_667:
	ds_read_b128 v[70:73], v117
	ds_read_b128 v[74:77], v117 offset:64
	ds_read_b128 v[78:81], v117 offset:2560
	ds_read_b128 v[86:89], v117 offset:2624
	ds_read_b128 v[82:85], v117 offset:5120
	ds_read_b128 v[122:125], v117 offset:5184
	ds_read_b128 v[90:93], v117 offset:7680
	ds_read_b128 v[126:129], v117 offset:7744
	s_add_i32 s59, s56, -1
	s_min_i32 s6, s59, s58
	s_cmp_ge_i32 s6, s55
	s_mov_b64 s[30:31], -1
	s_cbranch_scc0 .LBB0_669
	s_sub_i32 s0, s6, s55
	s_lshl_b64 s[10:11], s[0:1], 13
	s_add_u32 s0, s24, s10
	s_addc_u32 s7, s25, s11
	s_and_b64 s[8:9], s[28:29], exec
	s_cselect_b32 s9, 0, s7
	s_cselect_b32 s8, 0, s0
	s_add_u32 s10, s22, s10
	s_addc_u32 s11, s23, s11
	s_mov_b64 s[30:31], 0

.LBB0_671:
	s_cmp_eq_u64 s[8:9], 0
	v_lshl_add_u64 v[62:63], s[8:9], 0, v[110:111]
	v_lshl_add_u64 v[66:67], s[10:11], 0, v[110:111]
	s_cselect_b64 s[6:7], -1, 0
	v_cndmask_b32_e64 v63, v63, v67, s[6:7]
	v_cndmask_b32_e64 v62, v62, v66, s[6:7]
	global_load_dwordx4 v[62:65], v[62:63], off
	global_load_dwordx4 v[66:69], v[66:67], off
	s_setprio 1
	s_waitcnt lgkmcnt(7)
	v_mfma_f32_16x16x32_bf16 v[94:97], v[70:73], v[18:21], 0
	v_mfma_f32_16x16x32_bf16 v[70:73], v[70:73], v[26:29], 0
	s_waitcnt lgkmcnt(5)
	v_mfma_f32_16x16x32_bf16 v[130:133], v[78:81], v[18:21], 0
	v_mfma_f32_16x16x32_bf16 v[78:81], v[78:81], v[26:29], 0
	s_waitcnt lgkmcnt(3)
	v_mfma_f32_16x16x32_bf16 v[134:137], v[82:85], v[18:21], 0
	v_mfma_f32_16x16x32_bf16 v[138:141], v[82:85], v[26:29], 0
	s_waitcnt lgkmcnt(1)
	v_mfma_f32_16x16x32_bf16 v[142:145], v[90:93], v[18:21], 0
	v_mfma_f32_16x16x32_bf16 v[146:149], v[90:93], v[26:29], 0
	v_mfma_f32_16x16x32_bf16 v[98:101], v[74:77], v[22:25], v[94:97]
	v_mfma_f32_16x16x32_bf16 v[82:85], v[74:77], v[30:33], v[70:73]
	v_mfma_f32_16x16x32_bf16 v[94:97], v[86:89], v[22:25], v[130:133]
	v_mfma_f32_16x16x32_bf16 v[78:81], v[86:89], v[30:33], v[78:81]
	v_mfma_f32_16x16x32_bf16 v[90:93], v[122:125], v[22:25], v[134:137]
	v_mfma_f32_16x16x32_bf16 v[74:77], v[122:125], v[30:33], v[138:141]
	s_waitcnt lgkmcnt(0)
	v_mfma_f32_16x16x32_bf16 v[86:89], v[126:129], v[22:25], v[142:145]
	v_mfma_f32_16x16x32_bf16 v[70:73], v[126:129], v[30:33], v[146:149]
	s_setprio 0
	v_max3_f32 v102, v98, s48, v99
	v_max3_f32 v102, v102, v100, v101
	v_max3_f32 v102, v102, v94, v95
	v_max3_f32 v102, v102, v96, v97
	v_max3_f32 v102, v102, v90, v91
	v_max3_f32 v102, v102, v92, v93
	v_max3_f32 v102, v102, v86, v87
	v_max3_f32 v102, v102, v88, v89
	v_mul_f32_e32 v122, 0x3e38aa3b, v102
	v_max3_f32 v102, v82, s48, v83
	v_max3_f32 v102, v102, v84, v85
	v_max3_f32 v102, v102, v78, v79
	v_max3_f32 v102, v102, v80, v81
	v_max3_f32 v102, v102, v74, v75
	v_max3_f32 v102, v102, v76, v77
	v_max3_f32 v102, v102, v70, v71
	v_max3_f32 v102, v102, v72, v73
	v_add_f32_e32 v123, 0x41800000, v120
	v_mul_f32_e32 v102, 0x3e38aa3b, v102
	v_cmp_gt_f32_e32 vcc, v122, v123
	v_add_f32_e32 v123, 0x41800000, v119
	v_cmp_gt_f32_e64 s[8:9], v102, v123
	s_or_b64 vcc, vcc, s[8:9]
	s_cbranch_vccz .LBB0_673
	ds_bpermute_b32 v123, v112, v122
	v_max_f32_e32 v122, v122, v122
	ds_bpermute_b32 v124, v112, v102
	v_max_f32_e32 v125, v102, v102
	s_waitcnt lgkmcnt(1)
	v_max_f32_e32 v123, v123, v123
	v_max_f32_e32 v122, v122, v123
	ds_bpermute_b32 v123, v113, v122
	s_waitcnt lgkmcnt(0)
	v_max3_f32 v126, v120, v122, v123
	v_sub_f32_e32 v102, v120, v126
	v_max_f32_e32 v120, v124, v124
	v_max_f32_e32 v120, v125, v120
	ds_bpermute_b32 v122, v113, v120
	v_exp_f32_e32 v102, v102
	s_waitcnt lgkmcnt(0)
	v_max3_f32 v124, v119, v120, v122
	v_sub_f32_e32 v119, v119, v124
	v_exp_f32_e32 v122, v119
	v_mov_b32_e32 v123, v102
	v_pk_mul_f32 v[52:53], v[52:53], v[102:103] op_sel_hi:[1,0]
	v_pk_mul_f32 v[50:51], v[50:51], v[102:103] op_sel_hi:[1,0]
	v_pk_mul_f32 v[46:47], v[46:47], v[102:103] op_sel_hi:[1,0]
	v_pk_mul_f32 v[44:45], v[44:45], v[102:103] op_sel_hi:[1,0]
	v_pk_mul_f32 v[40:41], v[40:41], v[102:103] op_sel_hi:[1,0]
	v_pk_mul_f32 v[38:39], v[38:39], v[102:103] op_sel_hi:[1,0]
	v_pk_mul_f32 v[36:37], v[36:37], v[102:103] op_sel_hi:[1,0]
	v_pk_mul_f32 v[34:35], v[34:35], v[102:103] op_sel_hi:[1,0]
	v_pk_mul_f32 v[108:109], v[108:109], v[122:123]
	v_pk_mul_f32 v[16:17], v[16:17], v[122:123] op_sel_hi:[1,0]
	v_pk_mul_f32 v[14:15], v[14:15], v[122:123] op_sel_hi:[1,0]
	v_pk_mul_f32 v[12:13], v[12:13], v[122:123] op_sel_hi:[1,0]
	v_pk_mul_f32 v[10:11], v[10:11], v[122:123] op_sel_hi:[1,0]
	v_pk_mul_f32 v[8:9], v[8:9], v[122:123] op_sel_hi:[1,0]
	v_pk_mul_f32 v[6:7], v[6:7], v[122:123] op_sel_hi:[1,0]
	v_pk_mul_f32 v[4:5], v[4:5], v[122:123] op_sel_hi:[1,0]
	v_pk_mul_f32 v[2:3], v[2:3], v[122:123] op_sel_hi:[1,0]
	v_mov_b32_e32 v120, v126
	v_mov_b32_e32 v119, v124

.LBB0_737:
	s_mov_b64 s[6:7], 0
	s_barrier

.LBB0_903:
	s_or_b64 exec, exec, s[36:37]
	s_mov_b64 s[6:7], 0
	s_barrier

.LBB0_956:
	s_mul_hi_u32 s0, s67, 0x580
	s_mul_i32 s0, s0, s66
	s_sub_i32 s0, 0x580, s0
	s_sub_i32 s1, s0, s66
	s_cmp_ge_u32 s0, s66
	s_cselect_b32 s0, s1, s0
	s_sub_i32 s1, s0, s66
	s_cmp_ge_u32 s0, s66
	s_cselect_b32 s3, s1, s0
	s_cmp_lt_i32 s83, s3
	s_cbranch_scc1 .Ltail1_unitwg
	s_sub_i32 s2, s83, s3
	s_movk_i32 s98, 0x4d0
	s_sub_i32 s99, s84, s3
	s_branch .Ltail1_common
.Ltail1_unitwg:
	s_add_i32 s2, s83, 0x4d0
	s_movk_i32 s98, 0x6d0
	s_mov_b32 s99, s3
.Ltail1_common:
	s_cmp_ge_i32 s2, s98
	s_cbranch_scc1 .LBB0_1041
	v_readlane_b32 s6, v254, 0
	v_readlane_b32 s7, v254, 1
	s_load_dwordx2 s[0:1], s[6:7], 0xf0
	s_mov_b32 s3, s99
	s_load_dwordx2 s[4:5], s[6:7], 0xe0
	s_load_dwordx2 s[20:21], s[6:7], 0xc8
	s_load_dwordx4 s[8:11], s[6:7], 0x40
	s_load_dwordx2 s[26:27], s[6:7], 0x50
	s_load_dwordx4 s[12:15], s[6:7], 0xb0
	s_load_dwordx4 s[16:19], s[6:7], 0x78
	s_movk_i32 s53, 0x2b0
	s_waitcnt lgkmcnt(0)
	s_add_u32 s33, s0, 0x2c80000
	s_addc_u32 s48, s1, 0
	s_add_u32 s49, s0, 0x1680000
	s_addc_u32 s50, s1, 0
	s_add_u32 s22, s0, 0x1480000
	s_addc_u32 s23, s1, 0
	s_add_u32 s24, s0, 0xe80000
	s_addc_u32 s25, s1, 0
	s_add_u32 s28, s0, 0xb80000
	s_addc_u32 s29, s1, 0
	s_add_u32 s30, s0, 0x400000
	s_addc_u32 s31, s1, 0
	s_add_u32 s51, s0, 0x78000
	s_addc_u32 s52, s1, 0
	s_mov_b32 s35, 0
	v_mov_b32_e32 v87, 0
	s_movk_i32 s54, 0x404
	s_movk_i32 s55, 0xfa50
	s_mov_b32 s56, 0x3780000
	s_mov_b64 s[36:37], 0x1000
	s_mov_b32 s57, 0x4080000
	s_movk_i32 s58, 0x104
	s_movk_i32 s59, 0x3c00
	s_mov_b32 s60, 0x20000
	s_mov_b32 s61, 0x40000
	s_movk_i32 s62, 0x47f
	s_movk_i32 s63, 0x27f
	s_movk_i32 s64, 0x6000
	s_mov_b32 s65, 0xc000
	s_mov_b32 s66, 0x12000
	s_mov_b32 s67, 0x18000
	s_mov_b32 s68, 0x1e000
	s_mov_b32 s69, 0x24000
	s_mov_b32 s71, 0x2a000
	s_movk_i32 s72, 0x2400
	s_movk_i32 s73, 0x900
	s_movk_i32 s74, 0x1ff
	s_movk_i32 s75, 0x6ff
	v_mov_b32_e32 v1, 0x3e000000
	s_branch .LBB0_961

.LBB0_960:
	s_add_i32 s2, s2, s3
	s_cmp_lt_i32 s2, s98
	s_cbranch_scc0 .LBB0_1041

.LBB0_1134:
	v_lshl_or_b32 v148, v167, 2, s30
	v_mad_u64_u32 v[148:149], s[24:25], v168, s56, v[148:149]
	v_cvt_pk_bf16_f32 v98, v98, v99
	v_cvt_pk_bf16_f32 v99, v100, v101
	v_cvt_pk_bf16_f32 v66, v66, v67
	v_cvt_pk_bf16_f32 v58, v58, v59
	v_cvt_pk_bf16_f32 v59, v60, v61
	s_nop 0
	v_lshl_add_u32 v147, v148, 1, 0
	v_add_u32_e32 v100, 0x6000, v147
	v_add_u32_e32 v60, 0x10820, v147
	v_cvt_pk_bf16_f32 v50, v50, v51
	v_cvt_pk_bf16_f32 v51, v52, v53
	v_add_u32_e32 v52, 0x12920, v147
	v_cvt_pk_bf16_f32 v42, v42, v43
	v_cvt_pk_bf16_f32 v43, v44, v45
	v_add_u32_e32 v44, 0x14a20, v147
	v_cvt_pk_bf16_f32 v34, v34, v35
	v_cvt_pk_bf16_f32 v35, v36, v37
	v_add_u32_e32 v36, 0x16b20, v147
	v_cvt_pk_bf16_f32 v26, v26, v27
	v_cvt_pk_bf16_f32 v27, v28, v29
	v_add_u32_e32 v28, 0x10920, v147
	v_cvt_pk_bf16_f32 v18, v18, v19
	v_cvt_pk_bf16_f32 v19, v20, v21
	v_add_u32_e32 v20, 0x12a20, v147
	v_cvt_pk_bf16_f32 v10, v10, v11
	v_cvt_pk_bf16_f32 v11, v12, v13
	v_add_u32_e32 v12, 0x14b20, v147
	s_lshl_b32 s7, s58, 8
	v_cvt_pk_bf16_f32 v114, v114, v115
	v_cvt_pk_bf16_f32 v115, v116, v117
	v_add_u32_e32 v116, 0x2000, v147
	v_cvt_pk_bf16_f32 v106, v106, v107
	v_cvt_pk_bf16_f32 v107, v108, v109
	v_add_u32_e32 v108, 0x4000, v147
	v_cvt_pk_bf16_f32 v70, v70, v71
	v_cvt_pk_bf16_f32 v71, v72, v73
	v_cvt_pk_bf16_f32 v67, v68, v69
	ds_write2_b64 v100, v[70:71], v[66:67] offset0:128 offset1:132
	v_add_u32_e32 v66, 0x10800, v147
	ds_write_b64 v60, v[58:59]
	v_add_u32_e32 v58, 0x12900, v147
	ds_write_b64 v52, v[50:51]
	v_add_u32_e32 v50, 0x14a00, v147
	ds_write_b64 v44, v[42:43]
	v_add_u32_e32 v42, 0x16b00, v147
	ds_write_b64 v36, v[34:35]
	v_add_u32_e32 v34, 0x10900, v147
	ds_write_b64 v28, v[26:27]
	v_add_u32_e32 v26, 0x12a00, v147
	ds_write_b64 v20, v[18:19]
	v_add_u32_e32 v18, 0x14b00, v147
	ds_write_b64 v12, v[10:11]
	v_add_u32_e32 v10, 0x16c00, v147
	v_cvt_pk_bf16_f32 v2, v2, v3
	v_cvt_pk_bf16_f32 v3, v4, v5
	v_add_u32_e32 v4, 0x16c20, v147
	s_lshl_b32 s24, s59, 1
	s_mov_b32 s25, 0
	v_cvt_pk_bf16_f32 v126, v126, v127
	v_cvt_pk_bf16_f32 v127, v128, v129
	v_cvt_pk_bf16_f32 v122, v122, v123
	v_cvt_pk_bf16_f32 v123, v124, v125
	ds_write2_b64 v147, v[126:127], v[122:123] offset1:4
	v_cvt_pk_bf16_f32 v118, v118, v119
	v_cvt_pk_bf16_f32 v119, v120, v121
	ds_write2_b64 v116, v[118:119], v[114:115] offset0:32 offset1:36
	v_cvt_pk_bf16_f32 v110, v110, v111
	v_cvt_pk_bf16_f32 v111, v112, v113
	ds_write2_b64 v108, v[110:111], v[106:107] offset0:64 offset1:68
	v_cvt_pk_bf16_f32 v102, v102, v103
	v_cvt_pk_bf16_f32 v103, v104, v105
	ds_write2_b64 v100, v[102:103], v[98:99] offset0:96 offset1:100
	v_cvt_pk_bf16_f32 v94, v94, v95
	v_cvt_pk_bf16_f32 v95, v96, v97
	v_cvt_pk_bf16_f32 v90, v90, v91
	v_cvt_pk_bf16_f32 v91, v92, v93
	ds_write2_b64 v147, v[94:95], v[90:91] offset0:32 offset1:36
	v_cvt_pk_bf16_f32 v86, v86, v87
	v_cvt_pk_bf16_f32 v87, v88, v89
	v_cvt_pk_bf16_f32 v82, v82, v83
	v_cvt_pk_bf16_f32 v83, v84, v85
	ds_write2_b64 v116, v[86:87], v[82:83] offset0:64 offset1:68
	v_cvt_pk_bf16_f32 v78, v78, v79
	v_cvt_pk_bf16_f32 v79, v80, v81
	v_cvt_pk_bf16_f32 v74, v74, v75
	v_cvt_pk_bf16_f32 v75, v76, v77
	ds_write2_b64 v108, v[78:79], v[74:75] offset0:96 offset1:100
	v_cvt_pk_bf16_f32 v62, v62, v63
	v_cvt_pk_bf16_f32 v63, v64, v65
	ds_write_b64 v66, v[62:63]
	v_cvt_pk_bf16_f32 v54, v54, v55
	v_cvt_pk_bf16_f32 v55, v56, v57
	ds_write_b64 v58, v[54:55]
	v_cvt_pk_bf16_f32 v46, v46, v47
	v_cvt_pk_bf16_f32 v47, v48, v49
	ds_write_b64 v50, v[46:47]
	v_cvt_pk_bf16_f32 v38, v38, v39
	v_cvt_pk_bf16_f32 v39, v40, v41
	ds_write_b64 v42, v[38:39]
	v_cvt_pk_bf16_f32 v30, v30, v31
	v_cvt_pk_bf16_f32 v31, v32, v33
	ds_write_b64 v34, v[30:31]
	v_cvt_pk_bf16_f32 v22, v22, v23
	v_cvt_pk_bf16_f32 v23, v24, v25
	ds_write_b64 v26, v[22:23]
	v_cvt_pk_bf16_f32 v14, v14, v15
	v_cvt_pk_bf16_f32 v15, v16, v17
	ds_write_b64 v18, v[14:15]
	v_cvt_pk_bf16_f32 v6, v6, v7
	v_cvt_pk_bf16_f32 v7, v8, v9
	ds_write_b64 v10, v[6:7]
	ds_write_b64 v4, v[2:3]
	v_lshlrev_b32_e32 v2, 3, v0
	v_and_b32_e32 v2, 0x78, v2
	v_lshrrev_b32_e32 v3, 4, v0
	v_mul_u32_u24_e32 v4, 0x210, v3
	v_lshl_add_u32 v4, v2, 1, v4
	v_add_u32_e32 v5, 0x10800, v4
	s_add_i32 s28, s24, 0
	s_lshl_b32 s29, s28, 7
	s_add_i32 s30, s29, 0xffffe000
	s_ashr_i32 s30, s30, 10
	s_cmp_gt_i32 s28, 63
	s_cselect_b32 s30, s30, 8
	s_mul_i32 s30, s30, 0x6000
	s_add_u32 s26, s0, s30
	s_addc_u32 s27, s1, 0
	s_add_u32 s26, s26, 0xd000
	s_addc_u32 s27, s27, 0
	v_add_u32_e32 v122, s29, v3
	v_lshlrev_b32_e32 v122, 11, v122
	s_mov_b32 s25, s7
	v_or_b32_e32 v123, s25, v2
	v_lshlrev_b32_e32 v22, 2, v123
	v_lshl_add_u32 v6, v123, 1, v122
	v_add_u32_e32 v7, 0x10000, v6
	v_add_u32_e32 v8, 0x20000, v6
	v_add_u32_e32 v9, 0x30000, v6
	global_load_dwordx4 v[26:29], v6, s[4:5]
	global_load_dwordx4 v[30:33], v7, s[4:5]
	global_load_dwordx4 v[34:37], v8, s[4:5]
	global_load_dwordx4 v[38:41], v9, s[4:5]
	global_load_dwordx4 v[90:93], v22, s[26:27]
	global_load_dwordx4 v[94:97], v22, s[26:27] offset:16
	s_or_b32 s25, s7, 0x80
	v_or_b32_e32 v123, s25, v2
	v_lshlrev_b32_e32 v23, 2, v123
	v_lshl_add_u32 v10, v123, 1, v122
	v_add_u32_e32 v11, 0x10000, v10
	v_add_u32_e32 v12, 0x20000, v10
	v_add_u32_e32 v13, 0x30000, v10
	global_load_dwordx4 v[42:45], v10, s[4:5]
	global_load_dwordx4 v[46:49], v11, s[4:5]
	global_load_dwordx4 v[50:53], v12, s[4:5]
	global_load_dwordx4 v[54:57], v13, s[4:5]
	global_load_dwordx4 v[98:101], v23, s[26:27]
	global_load_dwordx4 v[102:105], v23, s[26:27] offset:16
	s_add_i32 s28, s24, 1
	s_lshl_b32 s29, s28, 7
	s_add_i32 s30, s29, 0xffffe000
	s_ashr_i32 s30, s30, 10
	s_cmp_gt_i32 s28, 63
	s_cselect_b32 s30, s30, 8
	s_mul_i32 s30, s30, 0x6000
	s_add_u32 s26, s0, s30
	s_addc_u32 s27, s1, 0
	s_add_u32 s26, s26, 0xd000
	s_addc_u32 s27, s27, 0
	v_add_u32_e32 v122, s29, v3
	v_lshlrev_b32_e32 v122, 11, v122
	s_mov_b32 s25, s7
	v_or_b32_e32 v123, s25, v2
	v_lshlrev_b32_e32 v24, 2, v123
	v_lshl_add_u32 v14, v123, 1, v122
	v_add_u32_e32 v15, 0x10000, v14
	v_add_u32_e32 v16, 0x20000, v14
	v_add_u32_e32 v17, 0x30000, v14
	global_load_dwordx4 v[58:61], v14, s[4:5]
	global_load_dwordx4 v[62:65], v15, s[4:5]
	global_load_dwordx4 v[66:69], v16, s[4:5]
	global_load_dwordx4 v[70:73], v17, s[4:5]
	global_load_dwordx4 v[106:109], v24, s[26:27]
	global_load_dwordx4 v[110:113], v24, s[26:27] offset:16
	s_or_b32 s25, s7, 0x80
	v_or_b32_e32 v123, s25, v2
	v_lshlrev_b32_e32 v25, 2, v123
	v_lshl_add_u32 v18, v123, 1, v122
	v_add_u32_e32 v19, 0x10000, v18
	v_add_u32_e32 v20, 0x20000, v18
	v_add_u32_e32 v21, 0x30000, v18
	global_load_dwordx4 v[74:77], v18, s[4:5]
	global_load_dwordx4 v[78:81], v19, s[4:5]
	global_load_dwordx4 v[82:85], v20, s[4:5]
	global_load_dwordx4 v[86:89], v21, s[4:5]
	global_load_dwordx4 v[114:117], v25, s[26:27]
	global_load_dwordx4 v[118:121], v25, s[26:27] offset:16
	s_waitcnt lgkmcnt(0)
	s_barrier
.LBB0_1135:
	ds_read_b128 v[172:175], v4
	ds_read_b128 v[176:179], v4 offset:16896
	ds_read_b128 v[180:183], v4 offset:33792
	ds_read_b128 v[184:187], v4 offset:50688
	s_waitcnt lgkmcnt(3)
	v_lshlrev_b32_e32 v188, 16, v172
	v_and_b32_e32 v189, 0xffff0000, v172
	v_lshlrev_b32_e32 v190, 16, v173
	v_and_b32_e32 v191, 0xffff0000, v173
	v_lshlrev_b32_e32 v192, 16, v174
	v_and_b32_e32 v193, 0xffff0000, v174
	v_lshlrev_b32_e32 v194, 16, v175
	v_and_b32_e32 v195, 0xffff0000, v175
	s_waitcnt vmcnt(18)
	v_lshlrev_b32_e32 v196, 16, v26
	v_and_b32_e32 v197, 0xffff0000, v26
	v_lshlrev_b32_e32 v198, 16, v27
	v_and_b32_e32 v199, 0xffff0000, v27
	v_lshlrev_b32_e32 v200, 16, v28
	v_and_b32_e32 v201, 0xffff0000, v28
	v_lshlrev_b32_e32 v202, 16, v29
	v_and_b32_e32 v203, 0xffff0000, v29
	v_fmac_f32_e32 v196, v90, v188
	v_fmac_f32_e32 v197, v91, v189
	v_fmac_f32_e32 v198, v92, v190
	v_fmac_f32_e32 v199, v93, v191
	v_fmac_f32_e32 v200, v94, v192
	v_fmac_f32_e32 v201, v95, v193
	v_fmac_f32_e32 v202, v96, v194
	v_fmac_f32_e32 v203, v97, v195
	v_cvt_pk_bf16_f32 v26, v196, v197
	v_cvt_pk_bf16_f32 v27, v198, v199
	v_cvt_pk_bf16_f32 v28, v200, v201
	v_cvt_pk_bf16_f32 v29, v202, v203
	global_store_dwordx4 v6, v[26:29], s[4:5]
	s_waitcnt lgkmcnt(2)
	v_lshlrev_b32_e32 v188, 16, v176
	v_and_b32_e32 v189, 0xffff0000, v176
	v_lshlrev_b32_e32 v190, 16, v177
	v_and_b32_e32 v191, 0xffff0000, v177
	v_lshlrev_b32_e32 v192, 16, v178
	v_and_b32_e32 v193, 0xffff0000, v178
	v_lshlrev_b32_e32 v194, 16, v179
	v_and_b32_e32 v195, 0xffff0000, v179
	v_lshlrev_b32_e32 v196, 16, v30
	v_and_b32_e32 v197, 0xffff0000, v30
	v_lshlrev_b32_e32 v198, 16, v31
	v_and_b32_e32 v199, 0xffff0000, v31
	v_lshlrev_b32_e32 v200, 16, v32
	v_and_b32_e32 v201, 0xffff0000, v32
	v_lshlrev_b32_e32 v202, 16, v33
	v_and_b32_e32 v203, 0xffff0000, v33
	v_fmac_f32_e32 v196, v90, v188
	v_fmac_f32_e32 v197, v91, v189
	v_fmac_f32_e32 v198, v92, v190
	v_fmac_f32_e32 v199, v93, v191
	v_fmac_f32_e32 v200, v94, v192
	v_fmac_f32_e32 v201, v95, v193
	v_fmac_f32_e32 v202, v96, v194
	v_fmac_f32_e32 v203, v97, v195
	v_cvt_pk_bf16_f32 v30, v196, v197
	v_cvt_pk_bf16_f32 v31, v198, v199
	v_cvt_pk_bf16_f32 v32, v200, v201
	v_cvt_pk_bf16_f32 v33, v202, v203
	global_store_dwordx4 v7, v[30:33], s[4:5]
	s_waitcnt lgkmcnt(1)
	v_lshlrev_b32_e32 v188, 16, v180
	v_and_b32_e32 v189, 0xffff0000, v180
	v_lshlrev_b32_e32 v190, 16, v181
	v_and_b32_e32 v191, 0xffff0000, v181
	v_lshlrev_b32_e32 v192, 16, v182
	v_and_b32_e32 v193, 0xffff0000, v182
	v_lshlrev_b32_e32 v194, 16, v183
	v_and_b32_e32 v195, 0xffff0000, v183
	v_lshlrev_b32_e32 v196, 16, v34
	v_and_b32_e32 v197, 0xffff0000, v34
	v_lshlrev_b32_e32 v198, 16, v35
	v_and_b32_e32 v199, 0xffff0000, v35
	v_lshlrev_b32_e32 v200, 16, v36
	v_and_b32_e32 v201, 0xffff0000, v36
	v_lshlrev_b32_e32 v202, 16, v37
	v_and_b32_e32 v203, 0xffff0000, v37
	v_fmac_f32_e32 v196, v90, v188
	v_fmac_f32_e32 v197, v91, v189
	v_fmac_f32_e32 v198, v92, v190
	v_fmac_f32_e32 v199, v93, v191
	v_fmac_f32_e32 v200, v94, v192
	v_fmac_f32_e32 v201, v95, v193
	v_fmac_f32_e32 v202, v96, v194
	v_fmac_f32_e32 v203, v97, v195
	v_cvt_pk_bf16_f32 v34, v196, v197
	v_cvt_pk_bf16_f32 v35, v198, v199
	v_cvt_pk_bf16_f32 v36, v200, v201
	v_cvt_pk_bf16_f32 v37, v202, v203
	global_store_dwordx4 v8, v[34:37], s[4:5]
	s_waitcnt lgkmcnt(0)
	v_lshlrev_b32_e32 v188, 16, v184
	v_and_b32_e32 v189, 0xffff0000, v184
	v_lshlrev_b32_e32 v190, 16, v185
	v_and_b32_e32 v191, 0xffff0000, v185
	v_lshlrev_b32_e32 v192, 16, v186
	v_and_b32_e32 v193, 0xffff0000, v186
	v_lshlrev_b32_e32 v194, 16, v187
	v_and_b32_e32 v195, 0xffff0000, v187
	ds_read_b128 v[172:175], v4 offset:256
	ds_read_b128 v[176:179], v4 offset:17152
	ds_read_b128 v[180:183], v4 offset:34048
	ds_read_b128 v[184:187], v4 offset:50944
	v_lshlrev_b32_e32 v196, 16, v38
	v_and_b32_e32 v197, 0xffff0000, v38
	v_lshlrev_b32_e32 v198, 16, v39
	v_and_b32_e32 v199, 0xffff0000, v39
	v_lshlrev_b32_e32 v200, 16, v40
	v_and_b32_e32 v201, 0xffff0000, v40
	v_lshlrev_b32_e32 v202, 16, v41
	v_and_b32_e32 v203, 0xffff0000, v41
	v_fmac_f32_e32 v196, v90, v188
	v_fmac_f32_e32 v197, v91, v189
	v_fmac_f32_e32 v198, v92, v190
	v_fmac_f32_e32 v199, v93, v191
	v_fmac_f32_e32 v200, v94, v192
	v_fmac_f32_e32 v201, v95, v193
	v_fmac_f32_e32 v202, v96, v194
	v_fmac_f32_e32 v203, v97, v195
	v_cvt_pk_bf16_f32 v38, v196, v197
	v_cvt_pk_bf16_f32 v39, v198, v199
	v_cvt_pk_bf16_f32 v40, v200, v201
	v_cvt_pk_bf16_f32 v41, v202, v203
	global_store_dwordx4 v9, v[38:41], s[4:5]
	s_waitcnt lgkmcnt(3)
	v_lshlrev_b32_e32 v188, 16, v172
	v_and_b32_e32 v189, 0xffff0000, v172
	v_lshlrev_b32_e32 v190, 16, v173
	v_and_b32_e32 v191, 0xffff0000, v173
	v_lshlrev_b32_e32 v192, 16, v174
	v_and_b32_e32 v193, 0xffff0000, v174
	v_lshlrev_b32_e32 v194, 16, v175
	v_and_b32_e32 v195, 0xffff0000, v175
	s_waitcnt vmcnt(16)
	v_lshlrev_b32_e32 v196, 16, v42
	v_and_b32_e32 v197, 0xffff0000, v42
	v_lshlrev_b32_e32 v198, 16, v43
	v_and_b32_e32 v199, 0xffff0000, v43
	v_lshlrev_b32_e32 v200, 16, v44
	v_and_b32_e32 v201, 0xffff0000, v44
	v_lshlrev_b32_e32 v202, 16, v45
	v_and_b32_e32 v203, 0xffff0000, v45
	v_fmac_f32_e32 v196, v98, v188
	v_fmac_f32_e32 v197, v99, v189
	v_fmac_f32_e32 v198, v100, v190
	v_fmac_f32_e32 v199, v101, v191
	v_fmac_f32_e32 v200, v102, v192
	v_fmac_f32_e32 v201, v103, v193
	v_fmac_f32_e32 v202, v104, v194
	v_fmac_f32_e32 v203, v105, v195
	v_cvt_pk_bf16_f32 v42, v196, v197
	v_cvt_pk_bf16_f32 v43, v198, v199
	v_cvt_pk_bf16_f32 v44, v200, v201
	v_cvt_pk_bf16_f32 v45, v202, v203
	global_store_dwordx4 v10, v[42:45], s[4:5]
	s_waitcnt lgkmcnt(2)
	v_lshlrev_b32_e32 v188, 16, v176
	v_and_b32_e32 v189, 0xffff0000, v176
	v_lshlrev_b32_e32 v190, 16, v177
	v_and_b32_e32 v191, 0xffff0000, v177
	v_lshlrev_b32_e32 v192, 16, v178
	v_and_b32_e32 v193, 0xffff0000, v178
	v_lshlrev_b32_e32 v194, 16, v179
	v_and_b32_e32 v195, 0xffff0000, v179
	v_lshlrev_b32_e32 v196, 16, v46
	v_and_b32_e32 v197, 0xffff0000, v46
	v_lshlrev_b32_e32 v198, 16, v47
	v_and_b32_e32 v199, 0xffff0000, v47
	v_lshlrev_b32_e32 v200, 16, v48
	v_and_b32_e32 v201, 0xffff0000, v48
	v_lshlrev_b32_e32 v202, 16, v49
	v_and_b32_e32 v203, 0xffff0000, v49
	v_fmac_f32_e32 v196, v98, v188
	v_fmac_f32_e32 v197, v99, v189
	v_fmac_f32_e32 v198, v100, v190
	v_fmac_f32_e32 v199, v101, v191
	v_fmac_f32_e32 v200, v102, v192
	v_fmac_f32_e32 v201, v103, v193
	v_fmac_f32_e32 v202, v104, v194
	v_fmac_f32_e32 v203, v105, v195
	v_cvt_pk_bf16_f32 v46, v196, v197
	v_cvt_pk_bf16_f32 v47, v198, v199
	v_cvt_pk_bf16_f32 v48, v200, v201
	v_cvt_pk_bf16_f32 v49, v202, v203
	global_store_dwordx4 v11, v[46:49], s[4:5]
	s_waitcnt lgkmcnt(1)
	v_lshlrev_b32_e32 v188, 16, v180
	v_and_b32_e32 v189, 0xffff0000, v180
	v_lshlrev_b32_e32 v190, 16, v181
	v_and_b32_e32 v191, 0xffff0000, v181
	v_lshlrev_b32_e32 v192, 16, v182
	v_and_b32_e32 v193, 0xffff0000, v182
	v_lshlrev_b32_e32 v194, 16, v183
	v_and_b32_e32 v195, 0xffff0000, v183
	v_lshlrev_b32_e32 v196, 16, v50
	v_and_b32_e32 v197, 0xffff0000, v50
	v_lshlrev_b32_e32 v198, 16, v51
	v_and_b32_e32 v199, 0xffff0000, v51
	v_lshlrev_b32_e32 v200, 16, v52
	v_and_b32_e32 v201, 0xffff0000, v52
	v_lshlrev_b32_e32 v202, 16, v53
	v_and_b32_e32 v203, 0xffff0000, v53
	v_fmac_f32_e32 v196, v98, v188
	v_fmac_f32_e32 v197, v99, v189
	v_fmac_f32_e32 v198, v100, v190
	v_fmac_f32_e32 v199, v101, v191
	v_fmac_f32_e32 v200, v102, v192
	v_fmac_f32_e32 v201, v103, v193
	v_fmac_f32_e32 v202, v104, v194
	v_fmac_f32_e32 v203, v105, v195
	v_cvt_pk_bf16_f32 v50, v196, v197
	v_cvt_pk_bf16_f32 v51, v198, v199
	v_cvt_pk_bf16_f32 v52, v200, v201
	v_cvt_pk_bf16_f32 v53, v202, v203
	global_store_dwordx4 v12, v[50:53], s[4:5]
	s_waitcnt lgkmcnt(0)
	v_lshlrev_b32_e32 v188, 16, v184
	v_and_b32_e32 v189, 0xffff0000, v184
	v_lshlrev_b32_e32 v190, 16, v185
	v_and_b32_e32 v191, 0xffff0000, v185
	v_lshlrev_b32_e32 v192, 16, v186
	v_and_b32_e32 v193, 0xffff0000, v186
	v_lshlrev_b32_e32 v194, 16, v187
	v_and_b32_e32 v195, 0xffff0000, v187
	ds_read_b128 v[172:175], v5
	ds_read_b128 v[176:179], v5 offset:16896
	ds_read_b128 v[180:183], v5 offset:33792
	ds_read_b128 v[184:187], v5 offset:50688
	v_lshlrev_b32_e32 v196, 16, v54
	v_and_b32_e32 v197, 0xffff0000, v54
	v_lshlrev_b32_e32 v198, 16, v55
	v_and_b32_e32 v199, 0xffff0000, v55
	v_lshlrev_b32_e32 v200, 16, v56
	v_and_b32_e32 v201, 0xffff0000, v56
	v_lshlrev_b32_e32 v202, 16, v57
	v_and_b32_e32 v203, 0xffff0000, v57
	v_fmac_f32_e32 v196, v98, v188
	v_fmac_f32_e32 v197, v99, v189
	v_fmac_f32_e32 v198, v100, v190
	v_fmac_f32_e32 v199, v101, v191
	v_fmac_f32_e32 v200, v102, v192
	v_fmac_f32_e32 v201, v103, v193
	v_fmac_f32_e32 v202, v104, v194
	v_fmac_f32_e32 v203, v105, v195
	v_cvt_pk_bf16_f32 v54, v196, v197
	v_cvt_pk_bf16_f32 v55, v198, v199
	v_cvt_pk_bf16_f32 v56, v200, v201
	v_cvt_pk_bf16_f32 v57, v202, v203
	global_store_dwordx4 v13, v[54:57], s[4:5]
	s_waitcnt lgkmcnt(3)
	v_lshlrev_b32_e32 v188, 16, v172
	v_and_b32_e32 v189, 0xffff0000, v172
	v_lshlrev_b32_e32 v190, 16, v173
	v_and_b32_e32 v191, 0xffff0000, v173
	v_lshlrev_b32_e32 v192, 16, v174
	v_and_b32_e32 v193, 0xffff0000, v174
	v_lshlrev_b32_e32 v194, 16, v175
	v_and_b32_e32 v195, 0xffff0000, v175
	s_waitcnt vmcnt(14)
	v_lshlrev_b32_e32 v196, 16, v58
	v_and_b32_e32 v197, 0xffff0000, v58
	v_lshlrev_b32_e32 v198, 16, v59
	v_and_b32_e32 v199, 0xffff0000, v59
	v_lshlrev_b32_e32 v200, 16, v60
	v_and_b32_e32 v201, 0xffff0000, v60
	v_lshlrev_b32_e32 v202, 16, v61
	v_and_b32_e32 v203, 0xffff0000, v61
	v_fmac_f32_e32 v196, v106, v188
	v_fmac_f32_e32 v197, v107, v189
	v_fmac_f32_e32 v198, v108, v190
	v_fmac_f32_e32 v199, v109, v191
	v_fmac_f32_e32 v200, v110, v192
	v_fmac_f32_e32 v201, v111, v193
	v_fmac_f32_e32 v202, v112, v194
	v_fmac_f32_e32 v203, v113, v195
	v_cvt_pk_bf16_f32 v58, v196, v197
	v_cvt_pk_bf16_f32 v59, v198, v199
	v_cvt_pk_bf16_f32 v60, v200, v201
	v_cvt_pk_bf16_f32 v61, v202, v203
	global_store_dwordx4 v14, v[58:61], s[4:5]
	s_waitcnt lgkmcnt(2)
	v_lshlrev_b32_e32 v188, 16, v176
	v_and_b32_e32 v189, 0xffff0000, v176
	v_lshlrev_b32_e32 v190, 16, v177
	v_and_b32_e32 v191, 0xffff0000, v177
	v_lshlrev_b32_e32 v192, 16, v178
	v_and_b32_e32 v193, 0xffff0000, v178
	v_lshlrev_b32_e32 v194, 16, v179
	v_and_b32_e32 v195, 0xffff0000, v179
	v_lshlrev_b32_e32 v196, 16, v62
	v_and_b32_e32 v197, 0xffff0000, v62
	v_lshlrev_b32_e32 v198, 16, v63
	v_and_b32_e32 v199, 0xffff0000, v63
	v_lshlrev_b32_e32 v200, 16, v64
	v_and_b32_e32 v201, 0xffff0000, v64
	v_lshlrev_b32_e32 v202, 16, v65
	v_and_b32_e32 v203, 0xffff0000, v65
	v_fmac_f32_e32 v196, v106, v188
	v_fmac_f32_e32 v197, v107, v189
	v_fmac_f32_e32 v198, v108, v190
	v_fmac_f32_e32 v199, v109, v191
	v_fmac_f32_e32 v200, v110, v192
	v_fmac_f32_e32 v201, v111, v193
	v_fmac_f32_e32 v202, v112, v194
	v_fmac_f32_e32 v203, v113, v195
	v_cvt_pk_bf16_f32 v62, v196, v197
	v_cvt_pk_bf16_f32 v63, v198, v199
	v_cvt_pk_bf16_f32 v64, v200, v201
	v_cvt_pk_bf16_f32 v65, v202, v203
	global_store_dwordx4 v15, v[62:65], s[4:5]
	s_waitcnt lgkmcnt(1)
	v_lshlrev_b32_e32 v188, 16, v180
	v_and_b32_e32 v189, 0xffff0000, v180
	v_lshlrev_b32_e32 v190, 16, v181
	v_and_b32_e32 v191, 0xffff0000, v181
	v_lshlrev_b32_e32 v192, 16, v182
	v_and_b32_e32 v193, 0xffff0000, v182
	v_lshlrev_b32_e32 v194, 16, v183
	v_and_b32_e32 v195, 0xffff0000, v183
	v_lshlrev_b32_e32 v196, 16, v66
	v_and_b32_e32 v197, 0xffff0000, v66
	v_lshlrev_b32_e32 v198, 16, v67
	v_and_b32_e32 v199, 0xffff0000, v67
	v_lshlrev_b32_e32 v200, 16, v68
	v_and_b32_e32 v201, 0xffff0000, v68
	v_lshlrev_b32_e32 v202, 16, v69
	v_and_b32_e32 v203, 0xffff0000, v69
	v_fmac_f32_e32 v196, v106, v188
	v_fmac_f32_e32 v197, v107, v189
	v_fmac_f32_e32 v198, v108, v190
	v_fmac_f32_e32 v199, v109, v191
	v_fmac_f32_e32 v200, v110, v192
	v_fmac_f32_e32 v201, v111, v193
	v_fmac_f32_e32 v202, v112, v194
	v_fmac_f32_e32 v203, v113, v195
	v_cvt_pk_bf16_f32 v66, v196, v197
	v_cvt_pk_bf16_f32 v67, v198, v199
	v_cvt_pk_bf16_f32 v68, v200, v201
	v_cvt_pk_bf16_f32 v69, v202, v203
	global_store_dwordx4 v16, v[66:69], s[4:5]
	s_waitcnt lgkmcnt(0)
	v_lshlrev_b32_e32 v188, 16, v184
	v_and_b32_e32 v189, 0xffff0000, v184
	v_lshlrev_b32_e32 v190, 16, v185
	v_and_b32_e32 v191, 0xffff0000, v185
	v_lshlrev_b32_e32 v192, 16, v186
	v_and_b32_e32 v193, 0xffff0000, v186
	v_lshlrev_b32_e32 v194, 16, v187
	v_and_b32_e32 v195, 0xffff0000, v187
	ds_read_b128 v[172:175], v5 offset:256
	ds_read_b128 v[176:179], v5 offset:17152
	ds_read_b128 v[180:183], v5 offset:34048
	ds_read_b128 v[184:187], v5 offset:50944
	v_lshlrev_b32_e32 v196, 16, v70
	v_and_b32_e32 v197, 0xffff0000, v70
	v_lshlrev_b32_e32 v198, 16, v71
	v_and_b32_e32 v199, 0xffff0000, v71
	v_lshlrev_b32_e32 v200, 16, v72
	v_and_b32_e32 v201, 0xffff0000, v72
	v_lshlrev_b32_e32 v202, 16, v73
	v_and_b32_e32 v203, 0xffff0000, v73
	v_fmac_f32_e32 v196, v106, v188
	v_fmac_f32_e32 v197, v107, v189
	v_fmac_f32_e32 v198, v108, v190
	v_fmac_f32_e32 v199, v109, v191
	v_fmac_f32_e32 v200, v110, v192
	v_fmac_f32_e32 v201, v111, v193
	v_fmac_f32_e32 v202, v112, v194
	v_fmac_f32_e32 v203, v113, v195
	v_cvt_pk_bf16_f32 v70, v196, v197
	v_cvt_pk_bf16_f32 v71, v198, v199
	v_cvt_pk_bf16_f32 v72, v200, v201
	v_cvt_pk_bf16_f32 v73, v202, v203
	global_store_dwordx4 v17, v[70:73], s[4:5]
	s_waitcnt lgkmcnt(3)
	v_lshlrev_b32_e32 v188, 16, v172
	v_and_b32_e32 v189, 0xffff0000, v172
	v_lshlrev_b32_e32 v190, 16, v173
	v_and_b32_e32 v191, 0xffff0000, v173
	v_lshlrev_b32_e32 v192, 16, v174
	v_and_b32_e32 v193, 0xffff0000, v174
	v_lshlrev_b32_e32 v194, 16, v175
	v_and_b32_e32 v195, 0xffff0000, v175
	s_waitcnt vmcnt(12)
	v_lshlrev_b32_e32 v196, 16, v74
	v_and_b32_e32 v197, 0xffff0000, v74
	v_lshlrev_b32_e32 v198, 16, v75
	v_and_b32_e32 v199, 0xffff0000, v75
	v_lshlrev_b32_e32 v200, 16, v76
	v_and_b32_e32 v201, 0xffff0000, v76
	v_lshlrev_b32_e32 v202, 16, v77
	v_and_b32_e32 v203, 0xffff0000, v77
	v_fmac_f32_e32 v196, v114, v188
	v_fmac_f32_e32 v197, v115, v189
	v_fmac_f32_e32 v198, v116, v190
	v_fmac_f32_e32 v199, v117, v191
	v_fmac_f32_e32 v200, v118, v192
	v_fmac_f32_e32 v201, v119, v193
	v_fmac_f32_e32 v202, v120, v194
	v_fmac_f32_e32 v203, v121, v195
	v_cvt_pk_bf16_f32 v74, v196, v197
	v_cvt_pk_bf16_f32 v75, v198, v199
	v_cvt_pk_bf16_f32 v76, v200, v201
	v_cvt_pk_bf16_f32 v77, v202, v203
	global_store_dwordx4 v18, v[74:77], s[4:5]
	s_waitcnt lgkmcnt(2)
	v_lshlrev_b32_e32 v188, 16, v176
	v_and_b32_e32 v189, 0xffff0000, v176
	v_lshlrev_b32_e32 v190, 16, v177
	v_and_b32_e32 v191, 0xffff0000, v177
	v_lshlrev_b32_e32 v192, 16, v178
	v_and_b32_e32 v193, 0xffff0000, v178
	v_lshlrev_b32_e32 v194, 16, v179
	v_and_b32_e32 v195, 0xffff0000, v179
	v_lshlrev_b32_e32 v196, 16, v78
	v_and_b32_e32 v197, 0xffff0000, v78
	v_lshlrev_b32_e32 v198, 16, v79
	v_and_b32_e32 v199, 0xffff0000, v79
	v_lshlrev_b32_e32 v200, 16, v80
	v_and_b32_e32 v201, 0xffff0000, v80
	v_lshlrev_b32_e32 v202, 16, v81
	v_and_b32_e32 v203, 0xffff0000, v81
	v_fmac_f32_e32 v196, v114, v188
	v_fmac_f32_e32 v197, v115, v189
	v_fmac_f32_e32 v198, v116, v190
	v_fmac_f32_e32 v199, v117, v191
	v_fmac_f32_e32 v200, v118, v192
	v_fmac_f32_e32 v201, v119, v193
	v_fmac_f32_e32 v202, v120, v194
	v_fmac_f32_e32 v203, v121, v195
	v_cvt_pk_bf16_f32 v78, v196, v197
	v_cvt_pk_bf16_f32 v79, v198, v199
	v_cvt_pk_bf16_f32 v80, v200, v201
	v_cvt_pk_bf16_f32 v81, v202, v203
	global_store_dwordx4 v19, v[78:81], s[4:5]
	s_waitcnt lgkmcnt(1)
	v_lshlrev_b32_e32 v188, 16, v180
	v_and_b32_e32 v189, 0xffff0000, v180
	v_lshlrev_b32_e32 v190, 16, v181
	v_and_b32_e32 v191, 0xffff0000, v181
	v_lshlrev_b32_e32 v192, 16, v182
	v_and_b32_e32 v193, 0xffff0000, v182
	v_lshlrev_b32_e32 v194, 16, v183
	v_and_b32_e32 v195, 0xffff0000, v183
	v_lshlrev_b32_e32 v196, 16, v82
	v_and_b32_e32 v197, 0xffff0000, v82
	v_lshlrev_b32_e32 v198, 16, v83
	v_and_b32_e32 v199, 0xffff0000, v83
	v_lshlrev_b32_e32 v200, 16, v84
	v_and_b32_e32 v201, 0xffff0000, v84
	v_lshlrev_b32_e32 v202, 16, v85
	v_and_b32_e32 v203, 0xffff0000, v85
	v_fmac_f32_e32 v196, v114, v188
	v_fmac_f32_e32 v197, v115, v189
	v_fmac_f32_e32 v198, v116, v190
	v_fmac_f32_e32 v199, v117, v191
	v_fmac_f32_e32 v200, v118, v192
	v_fmac_f32_e32 v201, v119, v193
	v_fmac_f32_e32 v202, v120, v194
	v_fmac_f32_e32 v203, v121, v195
	v_cvt_pk_bf16_f32 v82, v196, v197
	v_cvt_pk_bf16_f32 v83, v198, v199
	v_cvt_pk_bf16_f32 v84, v200, v201
	v_cvt_pk_bf16_f32 v85, v202, v203
	global_store_dwordx4 v20, v[82:85], s[4:5]
	s_waitcnt lgkmcnt(0)
	v_lshlrev_b32_e32 v188, 16, v184
	v_and_b32_e32 v189, 0xffff0000, v184
	v_lshlrev_b32_e32 v190, 16, v185
	v_and_b32_e32 v191, 0xffff0000, v185
	v_lshlrev_b32_e32 v192, 16, v186
	v_and_b32_e32 v193, 0xffff0000, v186
	v_lshlrev_b32_e32 v194, 16, v187
	v_and_b32_e32 v195, 0xffff0000, v187
	v_lshlrev_b32_e32 v196, 16, v86
	v_and_b32_e32 v197, 0xffff0000, v86
	v_lshlrev_b32_e32 v198, 16, v87
	v_and_b32_e32 v199, 0xffff0000, v87
	v_lshlrev_b32_e32 v200, 16, v88
	v_and_b32_e32 v201, 0xffff0000, v88
	v_lshlrev_b32_e32 v202, 16, v89
	v_and_b32_e32 v203, 0xffff0000, v89
	v_fmac_f32_e32 v196, v114, v188
	v_fmac_f32_e32 v197, v115, v189
	v_fmac_f32_e32 v198, v116, v190
	v_fmac_f32_e32 v199, v117, v191
	v_fmac_f32_e32 v200, v118, v192
	v_fmac_f32_e32 v201, v119, v193
	v_fmac_f32_e32 v202, v120, v194
	v_fmac_f32_e32 v203, v121, v195
	v_cvt_pk_bf16_f32 v86, v196, v197
	v_cvt_pk_bf16_f32 v87, v198, v199
	v_cvt_pk_bf16_f32 v88, v200, v201
	v_cvt_pk_bf16_f32 v89, v202, v203
	global_store_dwordx4 v21, v[86:89], s[4:5]
	s_mov_b64 s[6:7], 0
	s_barrier
	s_branch .LBB0_1097

.LBB0_1651:
	v_lshl_or_b32 v148, v131, 2, s19
	v_mad_u64_u32 v[148:149], s[20:21], v166, s22, v[148:149]
	v_cvt_pk_bf16_f32 v98, v98, v99
	v_cvt_pk_bf16_f32 v99, v100, v101
	v_cvt_pk_bf16_f32 v66, v66, v67
	v_cvt_pk_bf16_f32 v58, v58, v59
	v_cvt_pk_bf16_f32 v59, v60, v61
	s_nop 0
	v_lshl_add_u32 v131, v148, 1, 0
	v_add_u32_e32 v100, 0x6000, v131
	v_add_u32_e32 v60, 0x10820, v131
	v_cvt_pk_bf16_f32 v50, v50, v51
	v_cvt_pk_bf16_f32 v51, v52, v53
	v_add_u32_e32 v52, 0x12920, v131
	v_cvt_pk_bf16_f32 v42, v42, v43
	v_cvt_pk_bf16_f32 v43, v44, v45
	v_add_u32_e32 v44, 0x14a20, v131
	v_cvt_pk_bf16_f32 v34, v34, v35
	v_cvt_pk_bf16_f32 v35, v36, v37
	v_add_u32_e32 v36, 0x16b20, v131
	v_cvt_pk_bf16_f32 v26, v26, v27
	v_cvt_pk_bf16_f32 v27, v28, v29
	v_add_u32_e32 v28, 0x10920, v131
	v_cvt_pk_bf16_f32 v18, v18, v19
	v_cvt_pk_bf16_f32 v19, v20, v21
	v_add_u32_e32 v20, 0x12a20, v131
	v_cvt_pk_bf16_f32 v10, v10, v11
	v_cvt_pk_bf16_f32 v11, v12, v13
	v_add_u32_e32 v12, 0x14b20, v131
	s_lshl_b32 s7, s16, 8
	v_cvt_pk_bf16_f32 v114, v114, v115
	v_cvt_pk_bf16_f32 v115, v116, v117
	v_add_u32_e32 v116, 0x2000, v131
	v_cvt_pk_bf16_f32 v106, v106, v107
	v_cvt_pk_bf16_f32 v107, v108, v109
	v_add_u32_e32 v108, 0x4000, v131
	v_cvt_pk_bf16_f32 v70, v70, v71
	v_cvt_pk_bf16_f32 v71, v72, v73
	v_cvt_pk_bf16_f32 v67, v68, v69
	ds_write2_b64 v100, v[70:71], v[66:67] offset0:128 offset1:132
	v_add_u32_e32 v66, 0x10800, v131
	ds_write_b64 v60, v[58:59]
	v_add_u32_e32 v58, 0x12900, v131
	ds_write_b64 v52, v[50:51]
	v_add_u32_e32 v50, 0x14a00, v131
	ds_write_b64 v44, v[42:43]
	v_add_u32_e32 v42, 0x16b00, v131
	ds_write_b64 v36, v[34:35]
	v_add_u32_e32 v34, 0x10900, v131
	ds_write_b64 v28, v[26:27]
	v_add_u32_e32 v26, 0x12a00, v131
	ds_write_b64 v20, v[18:19]
	v_add_u32_e32 v18, 0x14b00, v131
	ds_write_b64 v12, v[10:11]
	v_add_u32_e32 v10, 0x16c00, v131
	v_cvt_pk_bf16_f32 v2, v2, v3
	v_cvt_pk_bf16_f32 v3, v4, v5
	v_add_u32_e32 v4, 0x16c20, v131
	s_lshl_b32 s17, s18, 1
	s_mov_b32 s19, 0
	v_cvt_pk_bf16_f32 v126, v126, v127
	v_cvt_pk_bf16_f32 v127, v128, v129
	v_cvt_pk_bf16_f32 v122, v122, v123
	v_cvt_pk_bf16_f32 v123, v124, v125
	ds_write2_b64 v131, v[126:127], v[122:123] offset1:4
	v_cvt_pk_bf16_f32 v118, v118, v119
	v_cvt_pk_bf16_f32 v119, v120, v121
	ds_write2_b64 v116, v[118:119], v[114:115] offset0:32 offset1:36
	v_cvt_pk_bf16_f32 v110, v110, v111
	v_cvt_pk_bf16_f32 v111, v112, v113
	ds_write2_b64 v108, v[110:111], v[106:107] offset0:64 offset1:68
	v_cvt_pk_bf16_f32 v102, v102, v103
	v_cvt_pk_bf16_f32 v103, v104, v105
	ds_write2_b64 v100, v[102:103], v[98:99] offset0:96 offset1:100
	v_cvt_pk_bf16_f32 v94, v94, v95
	v_cvt_pk_bf16_f32 v95, v96, v97
	v_cvt_pk_bf16_f32 v90, v90, v91
	v_cvt_pk_bf16_f32 v91, v92, v93
	ds_write2_b64 v131, v[94:95], v[90:91] offset0:32 offset1:36
	v_cvt_pk_bf16_f32 v86, v86, v87
	v_cvt_pk_bf16_f32 v87, v88, v89
	v_cvt_pk_bf16_f32 v82, v82, v83
	v_cvt_pk_bf16_f32 v83, v84, v85
	ds_write2_b64 v116, v[86:87], v[82:83] offset0:64 offset1:68
	v_cvt_pk_bf16_f32 v78, v78, v79
	v_cvt_pk_bf16_f32 v79, v80, v81
	v_cvt_pk_bf16_f32 v74, v74, v75
	v_cvt_pk_bf16_f32 v75, v76, v77
	ds_write2_b64 v108, v[78:79], v[74:75] offset0:96 offset1:100
	v_cvt_pk_bf16_f32 v62, v62, v63
	v_cvt_pk_bf16_f32 v63, v64, v65
	ds_write_b64 v66, v[62:63]
	v_cvt_pk_bf16_f32 v54, v54, v55
	v_cvt_pk_bf16_f32 v55, v56, v57
	ds_write_b64 v58, v[54:55]
	v_cvt_pk_bf16_f32 v46, v46, v47
	v_cvt_pk_bf16_f32 v47, v48, v49
	ds_write_b64 v50, v[46:47]
	v_cvt_pk_bf16_f32 v38, v38, v39
	v_cvt_pk_bf16_f32 v39, v40, v41
	ds_write_b64 v42, v[38:39]
	v_cvt_pk_bf16_f32 v30, v30, v31
	v_cvt_pk_bf16_f32 v31, v32, v33
	ds_write_b64 v34, v[30:31]
	v_cvt_pk_bf16_f32 v22, v22, v23
	v_cvt_pk_bf16_f32 v23, v24, v25
	ds_write_b64 v26, v[22:23]
	v_cvt_pk_bf16_f32 v14, v14, v15
	v_cvt_pk_bf16_f32 v15, v16, v17
	ds_write_b64 v18, v[14:15]
	v_cvt_pk_bf16_f32 v6, v6, v7
	v_cvt_pk_bf16_f32 v7, v8, v9
	ds_write_b64 v10, v[6:7]
	ds_write_b64 v4, v[2:3]
	v_lshlrev_b32_e32 v2, 3, v0
	v_and_b32_e32 v2, 0x78, v2
	v_lshrrev_b32_e32 v3, 4, v0
	v_mul_u32_u24_e32 v4, 0x210, v3
	v_lshl_add_u32 v4, v2, 1, v4
	v_add_u32_e32 v5, 0x10800, v4
	s_add_i32 s24, s17, 0
	s_lshl_b32 s25, s24, 7
	s_add_i32 s26, s25, 0xffffe000
	s_ashr_i32 s26, s26, 10
	s_add_i32 s26, s26, 9
	s_cmp_gt_i32 s24, 63
	s_cselect_b32 s26, s26, 17
	s_mul_i32 s26, s26, 0x6000
	s_add_u32 s20, s0, s26
	s_addc_u32 s21, s1, 0
	s_add_u32 s20, s20, 0xa000
	s_addc_u32 s21, s21, 0
	v_add_u32_e32 v122, s25, v3
	v_lshlrev_b32_e32 v122, 11, v122
	s_mov_b32 s19, s7
	v_or_b32_e32 v123, s19, v2
	v_lshlrev_b32_e32 v22, 2, v123
	v_lshl_add_u32 v6, v123, 1, v122
	v_add_u32_e32 v7, 0x10000, v6
	v_add_u32_e32 v8, 0x20000, v6
	v_add_u32_e32 v9, 0x30000, v6
	global_load_dwordx4 v[26:29], v6, s[4:5]
	global_load_dwordx4 v[30:33], v7, s[4:5]
	global_load_dwordx4 v[34:37], v8, s[4:5]
	global_load_dwordx4 v[38:41], v9, s[4:5]
	global_load_dwordx4 v[90:93], v22, s[20:21]
	global_load_dwordx4 v[94:97], v22, s[20:21] offset:16
	s_or_b32 s19, s7, 0x80
	v_or_b32_e32 v123, s19, v2
	v_lshlrev_b32_e32 v23, 2, v123
	v_lshl_add_u32 v10, v123, 1, v122
	v_add_u32_e32 v11, 0x10000, v10
	v_add_u32_e32 v12, 0x20000, v10
	v_add_u32_e32 v13, 0x30000, v10
	global_load_dwordx4 v[42:45], v10, s[4:5]
	global_load_dwordx4 v[46:49], v11, s[4:5]
	global_load_dwordx4 v[50:53], v12, s[4:5]
	global_load_dwordx4 v[54:57], v13, s[4:5]
	global_load_dwordx4 v[98:101], v23, s[20:21]
	global_load_dwordx4 v[102:105], v23, s[20:21] offset:16
	s_add_i32 s24, s17, 1
	s_lshl_b32 s25, s24, 7
	s_add_i32 s26, s25, 0xffffe000
	s_ashr_i32 s26, s26, 10
	s_add_i32 s26, s26, 9
	s_cmp_gt_i32 s24, 63
	s_cselect_b32 s26, s26, 17
	s_mul_i32 s26, s26, 0x6000
	s_add_u32 s20, s0, s26
	s_addc_u32 s21, s1, 0
	s_add_u32 s20, s20, 0xa000
	s_addc_u32 s21, s21, 0
	v_add_u32_e32 v122, s25, v3
	v_lshlrev_b32_e32 v122, 11, v122
	s_mov_b32 s19, s7
	v_or_b32_e32 v123, s19, v2
	v_lshlrev_b32_e32 v24, 2, v123
	v_lshl_add_u32 v14, v123, 1, v122
	v_add_u32_e32 v15, 0x10000, v14
	v_add_u32_e32 v16, 0x20000, v14
	v_add_u32_e32 v17, 0x30000, v14
	global_load_dwordx4 v[58:61], v14, s[4:5]
	global_load_dwordx4 v[62:65], v15, s[4:5]
	global_load_dwordx4 v[66:69], v16, s[4:5]
	global_load_dwordx4 v[70:73], v17, s[4:5]
	global_load_dwordx4 v[106:109], v24, s[20:21]
	global_load_dwordx4 v[110:113], v24, s[20:21] offset:16
	s_or_b32 s19, s7, 0x80
	v_or_b32_e32 v123, s19, v2
	v_lshlrev_b32_e32 v25, 2, v123
	v_lshl_add_u32 v18, v123, 1, v122
	v_add_u32_e32 v19, 0x10000, v18
	v_add_u32_e32 v20, 0x20000, v18
	v_add_u32_e32 v21, 0x30000, v18
	global_load_dwordx4 v[74:77], v18, s[4:5]
	global_load_dwordx4 v[78:81], v19, s[4:5]
	global_load_dwordx4 v[82:85], v20, s[4:5]
	global_load_dwordx4 v[86:89], v21, s[4:5]
	global_load_dwordx4 v[114:117], v25, s[20:21]
	global_load_dwordx4 v[118:121], v25, s[20:21] offset:16
	s_waitcnt lgkmcnt(0)
	s_barrier

.LBB0_1777:
	s_or_b64 exec, exec, s[36:37]
	s_mov_b64 s[4:5], 0
	s_barrier

.LBB0_1920:
	v_lshl_or_b32 v146, v160, 2, s30
	v_mad_u64_u32 v[146:147], s[24:25], v161, s52, v[146:147]
	v_cvt_pk_bf16_f32 v98, v98, v99
	v_cvt_pk_bf16_f32 v99, v100, v101
	v_cvt_pk_bf16_f32 v66, v66, v67
	v_cvt_pk_bf16_f32 v58, v58, v59
	v_cvt_pk_bf16_f32 v59, v60, v61
	s_nop 0
	v_lshl_add_u32 v145, v146, 1, 0
	v_add_u32_e32 v100, 0x6000, v145
	v_add_u32_e32 v60, 0x10820, v145
	v_cvt_pk_bf16_f32 v50, v50, v51
	v_cvt_pk_bf16_f32 v51, v52, v53
	v_add_u32_e32 v52, 0x12920, v145
	v_cvt_pk_bf16_f32 v42, v42, v43
	v_cvt_pk_bf16_f32 v43, v44, v45
	v_add_u32_e32 v44, 0x14a20, v145
	v_cvt_pk_bf16_f32 v34, v34, v35
	v_cvt_pk_bf16_f32 v35, v36, v37
	v_add_u32_e32 v36, 0x16b20, v145
	v_cvt_pk_bf16_f32 v26, v26, v27
	v_cvt_pk_bf16_f32 v27, v28, v29
	v_add_u32_e32 v28, 0x10920, v145
	v_cvt_pk_bf16_f32 v18, v18, v19
	v_cvt_pk_bf16_f32 v19, v20, v21
	v_add_u32_e32 v20, 0x12a20, v145
	v_cvt_pk_bf16_f32 v10, v10, v11
	v_cvt_pk_bf16_f32 v11, v12, v13
	v_add_u32_e32 v12, 0x14b20, v145
	s_lshl_b32 s5, s55, 8
	v_cvt_pk_bf16_f32 v114, v114, v115
	v_cvt_pk_bf16_f32 v115, v116, v117
	v_add_u32_e32 v116, 0x2000, v145
	v_cvt_pk_bf16_f32 v106, v106, v107
	v_cvt_pk_bf16_f32 v107, v108, v109
	v_add_u32_e32 v108, 0x4000, v145
	v_cvt_pk_bf16_f32 v70, v70, v71
	v_cvt_pk_bf16_f32 v71, v72, v73
	v_cvt_pk_bf16_f32 v67, v68, v69
	ds_write2_b64 v100, v[70:71], v[66:67] offset0:128 offset1:132
	v_add_u32_e32 v66, 0x10800, v145
	ds_write_b64 v60, v[58:59]
	v_add_u32_e32 v58, 0x12900, v145
	ds_write_b64 v52, v[50:51]
	v_add_u32_e32 v50, 0x14a00, v145
	ds_write_b64 v44, v[42:43]
	v_add_u32_e32 v42, 0x16b00, v145
	ds_write_b64 v36, v[34:35]
	v_add_u32_e32 v34, 0x10900, v145
	ds_write_b64 v28, v[26:27]
	v_add_u32_e32 v26, 0x12a00, v145
	ds_write_b64 v20, v[18:19]
	v_add_u32_e32 v18, 0x14b00, v145
	ds_write_b64 v12, v[10:11]
	v_add_u32_e32 v10, 0x16c00, v145
	v_cvt_pk_bf16_f32 v2, v2, v3
	v_cvt_pk_bf16_f32 v3, v4, v5
	v_add_u32_e32 v4, 0x16c20, v145
	s_lshl_b32 s24, s56, 1
	s_mov_b32 s25, 0
	v_cvt_pk_bf16_f32 v126, v126, v127
	v_cvt_pk_bf16_f32 v127, v128, v129
	v_cvt_pk_bf16_f32 v122, v122, v123
	v_cvt_pk_bf16_f32 v123, v124, v125
	ds_write2_b64 v145, v[126:127], v[122:123] offset1:4
	v_cvt_pk_bf16_f32 v118, v118, v119
	v_cvt_pk_bf16_f32 v119, v120, v121
	ds_write2_b64 v116, v[118:119], v[114:115] offset0:32 offset1:36
	v_cvt_pk_bf16_f32 v110, v110, v111
	v_cvt_pk_bf16_f32 v111, v112, v113
	ds_write2_b64 v108, v[110:111], v[106:107] offset0:64 offset1:68
	v_cvt_pk_bf16_f32 v102, v102, v103
	v_cvt_pk_bf16_f32 v103, v104, v105
	ds_write2_b64 v100, v[102:103], v[98:99] offset0:96 offset1:100
	v_cvt_pk_bf16_f32 v94, v94, v95
	v_cvt_pk_bf16_f32 v95, v96, v97
	v_cvt_pk_bf16_f32 v90, v90, v91
	v_cvt_pk_bf16_f32 v91, v92, v93
	ds_write2_b64 v145, v[94:95], v[90:91] offset0:32 offset1:36
	v_cvt_pk_bf16_f32 v86, v86, v87
	v_cvt_pk_bf16_f32 v87, v88, v89
	v_cvt_pk_bf16_f32 v82, v82, v83
	v_cvt_pk_bf16_f32 v83, v84, v85
	ds_write2_b64 v116, v[86:87], v[82:83] offset0:64 offset1:68
	v_cvt_pk_bf16_f32 v78, v78, v79
	v_cvt_pk_bf16_f32 v79, v80, v81
	v_cvt_pk_bf16_f32 v74, v74, v75
	v_cvt_pk_bf16_f32 v75, v76, v77
	ds_write2_b64 v108, v[78:79], v[74:75] offset0:96 offset1:100
	v_cvt_pk_bf16_f32 v62, v62, v63
	v_cvt_pk_bf16_f32 v63, v64, v65
	ds_write_b64 v66, v[62:63]
	v_cvt_pk_bf16_f32 v54, v54, v55
	v_cvt_pk_bf16_f32 v55, v56, v57
	ds_write_b64 v58, v[54:55]
	v_cvt_pk_bf16_f32 v46, v46, v47
	v_cvt_pk_bf16_f32 v47, v48, v49
	ds_write_b64 v50, v[46:47]
	v_cvt_pk_bf16_f32 v38, v38, v39
	v_cvt_pk_bf16_f32 v39, v40, v41
	ds_write_b64 v42, v[38:39]
	v_cvt_pk_bf16_f32 v30, v30, v31
	v_cvt_pk_bf16_f32 v31, v32, v33
	ds_write_b64 v34, v[30:31]
	v_cvt_pk_bf16_f32 v22, v22, v23
	v_cvt_pk_bf16_f32 v23, v24, v25
	ds_write_b64 v26, v[22:23]
	v_cvt_pk_bf16_f32 v14, v14, v15
	v_cvt_pk_bf16_f32 v15, v16, v17
	ds_write_b64 v18, v[14:15]
	v_cvt_pk_bf16_f32 v6, v6, v7
	v_cvt_pk_bf16_f32 v7, v8, v9
	ds_write_b64 v10, v[6:7]
	ds_write_b64 v4, v[2:3]
	v_lshlrev_b32_e32 v2, 3, v0
	v_and_b32_e32 v2, 0x78, v2
	v_lshrrev_b32_e32 v3, 4, v0
	v_mul_u32_u24_e32 v4, 0x210, v3
	v_lshl_add_u32 v4, v2, 1, v4
	v_add_u32_e32 v5, 0x10800, v4
	s_add_i32 s28, s24, 0
	s_lshl_b32 s29, s28, 7
	s_add_i32 s30, s29, 0xffffe000
	s_ashr_i32 s30, s30, 10
	s_add_i32 s30, s30, 9
	s_cmp_gt_i32 s28, 63
	s_cselect_b32 s30, s30, 17
	s_mul_i32 s30, s30, 0x6000
	s_add_u32 s26, s0, s30
	s_addc_u32 s27, s1, 0
	s_add_u32 s26, s26, 0xd000
	s_addc_u32 s27, s27, 0
	v_add_u32_e32 v122, s29, v3
	v_lshlrev_b32_e32 v122, 11, v122
	s_mov_b32 s25, s5
	v_or_b32_e32 v123, s25, v2
	v_lshlrev_b32_e32 v22, 2, v123
	v_lshl_add_u32 v6, v123, 1, v122
	v_add_u32_e32 v7, 0x10000, v6
	v_add_u32_e32 v8, 0x20000, v6
	v_add_u32_e32 v9, 0x30000, v6
	global_load_dwordx4 v[26:29], v6, s[6:7]
	global_load_dwordx4 v[30:33], v7, s[6:7]
	global_load_dwordx4 v[34:37], v8, s[6:7]
	global_load_dwordx4 v[38:41], v9, s[6:7]
	global_load_dwordx4 v[90:93], v22, s[26:27]
	global_load_dwordx4 v[94:97], v22, s[26:27] offset:16
	s_or_b32 s25, s5, 0x80
	v_or_b32_e32 v123, s25, v2
	v_lshlrev_b32_e32 v23, 2, v123
	v_lshl_add_u32 v10, v123, 1, v122
	v_add_u32_e32 v11, 0x10000, v10
	v_add_u32_e32 v12, 0x20000, v10
	v_add_u32_e32 v13, 0x30000, v10
	global_load_dwordx4 v[42:45], v10, s[6:7]
	global_load_dwordx4 v[46:49], v11, s[6:7]
	global_load_dwordx4 v[50:53], v12, s[6:7]
	global_load_dwordx4 v[54:57], v13, s[6:7]
	global_load_dwordx4 v[98:101], v23, s[26:27]
	global_load_dwordx4 v[102:105], v23, s[26:27] offset:16
	s_add_i32 s28, s24, 1
	s_lshl_b32 s29, s28, 7
	s_add_i32 s30, s29, 0xffffe000
	s_ashr_i32 s30, s30, 10
	s_add_i32 s30, s30, 9
	s_cmp_gt_i32 s28, 63
	s_cselect_b32 s30, s30, 17
	s_mul_i32 s30, s30, 0x6000
	s_add_u32 s26, s0, s30
	s_addc_u32 s27, s1, 0
	s_add_u32 s26, s26, 0xd000
	s_addc_u32 s27, s27, 0
	v_add_u32_e32 v122, s29, v3
	v_lshlrev_b32_e32 v122, 11, v122
	s_mov_b32 s25, s5
	v_or_b32_e32 v123, s25, v2
	v_lshlrev_b32_e32 v24, 2, v123
	v_lshl_add_u32 v14, v123, 1, v122
	v_add_u32_e32 v15, 0x10000, v14
	v_add_u32_e32 v16, 0x20000, v14
	v_add_u32_e32 v17, 0x30000, v14
	global_load_dwordx4 v[58:61], v14, s[6:7]
	global_load_dwordx4 v[62:65], v15, s[6:7]
	global_load_dwordx4 v[66:69], v16, s[6:7]
	global_load_dwordx4 v[70:73], v17, s[6:7]
	global_load_dwordx4 v[106:109], v24, s[26:27]
	global_load_dwordx4 v[110:113], v24, s[26:27] offset:16
	s_or_b32 s25, s5, 0x80
	v_or_b32_e32 v123, s25, v2
	v_lshlrev_b32_e32 v25, 2, v123
	v_lshl_add_u32 v18, v123, 1, v122
	v_add_u32_e32 v19, 0x10000, v18
	v_add_u32_e32 v20, 0x20000, v18
	v_add_u32_e32 v21, 0x30000, v18
	global_load_dwordx4 v[74:77], v18, s[6:7]
	global_load_dwordx4 v[78:81], v19, s[6:7]
	global_load_dwordx4 v[82:85], v20, s[6:7]
	global_load_dwordx4 v[86:89], v21, s[6:7]
	global_load_dwordx4 v[114:117], v25, s[26:27]
	global_load_dwordx4 v[118:121], v25, s[26:27] offset:16
	s_waitcnt lgkmcnt(0)
	s_barrier
.LBB0_1921:
	ds_read_b128 v[172:175], v4
	ds_read_b128 v[176:179], v4 offset:16896
	ds_read_b128 v[180:183], v4 offset:33792
	ds_read_b128 v[184:187], v4 offset:50688
	s_waitcnt lgkmcnt(3)
	v_lshlrev_b32_e32 v188, 16, v172
	v_and_b32_e32 v189, 0xffff0000, v172
	v_lshlrev_b32_e32 v190, 16, v173
	v_and_b32_e32 v191, 0xffff0000, v173
	v_lshlrev_b32_e32 v192, 16, v174
	v_and_b32_e32 v193, 0xffff0000, v174
	v_lshlrev_b32_e32 v194, 16, v175
	v_and_b32_e32 v195, 0xffff0000, v175
	s_waitcnt vmcnt(18)
	v_lshlrev_b32_e32 v196, 16, v26
	v_and_b32_e32 v197, 0xffff0000, v26
	v_lshlrev_b32_e32 v198, 16, v27
	v_and_b32_e32 v199, 0xffff0000, v27
	v_lshlrev_b32_e32 v200, 16, v28
	v_and_b32_e32 v201, 0xffff0000, v28
	v_lshlrev_b32_e32 v202, 16, v29
	v_and_b32_e32 v203, 0xffff0000, v29
	v_fmac_f32_e32 v196, v90, v188
	v_fmac_f32_e32 v197, v91, v189
	v_fmac_f32_e32 v198, v92, v190
	v_fmac_f32_e32 v199, v93, v191
	v_fmac_f32_e32 v200, v94, v192
	v_fmac_f32_e32 v201, v95, v193
	v_fmac_f32_e32 v202, v96, v194
	v_fmac_f32_e32 v203, v97, v195
	v_cvt_pk_bf16_f32 v26, v196, v197
	v_cvt_pk_bf16_f32 v27, v198, v199
	v_cvt_pk_bf16_f32 v28, v200, v201
	v_cvt_pk_bf16_f32 v29, v202, v203
	global_store_dwordx4 v6, v[26:29], s[6:7]
	s_waitcnt lgkmcnt(2)
	v_lshlrev_b32_e32 v188, 16, v176
	v_and_b32_e32 v189, 0xffff0000, v176
	v_lshlrev_b32_e32 v190, 16, v177
	v_and_b32_e32 v191, 0xffff0000, v177
	v_lshlrev_b32_e32 v192, 16, v178
	v_and_b32_e32 v193, 0xffff0000, v178
	v_lshlrev_b32_e32 v194, 16, v179
	v_and_b32_e32 v195, 0xffff0000, v179
	v_lshlrev_b32_e32 v196, 16, v30
	v_and_b32_e32 v197, 0xffff0000, v30
	v_lshlrev_b32_e32 v198, 16, v31
	v_and_b32_e32 v199, 0xffff0000, v31
	v_lshlrev_b32_e32 v200, 16, v32
	v_and_b32_e32 v201, 0xffff0000, v32
	v_lshlrev_b32_e32 v202, 16, v33
	v_and_b32_e32 v203, 0xffff0000, v33
	v_fmac_f32_e32 v196, v90, v188
	v_fmac_f32_e32 v197, v91, v189
	v_fmac_f32_e32 v198, v92, v190
	v_fmac_f32_e32 v199, v93, v191
	v_fmac_f32_e32 v200, v94, v192
	v_fmac_f32_e32 v201, v95, v193
	v_fmac_f32_e32 v202, v96, v194
	v_fmac_f32_e32 v203, v97, v195
	v_cvt_pk_bf16_f32 v30, v196, v197
	v_cvt_pk_bf16_f32 v31, v198, v199
	v_cvt_pk_bf16_f32 v32, v200, v201
	v_cvt_pk_bf16_f32 v33, v202, v203
	global_store_dwordx4 v7, v[30:33], s[6:7]
	s_waitcnt lgkmcnt(1)
	v_lshlrev_b32_e32 v188, 16, v180
	v_and_b32_e32 v189, 0xffff0000, v180
	v_lshlrev_b32_e32 v190, 16, v181
	v_and_b32_e32 v191, 0xffff0000, v181
	v_lshlrev_b32_e32 v192, 16, v182
	v_and_b32_e32 v193, 0xffff0000, v182
	v_lshlrev_b32_e32 v194, 16, v183
	v_and_b32_e32 v195, 0xffff0000, v183
	v_lshlrev_b32_e32 v196, 16, v34
	v_and_b32_e32 v197, 0xffff0000, v34
	v_lshlrev_b32_e32 v198, 16, v35
	v_and_b32_e32 v199, 0xffff0000, v35
	v_lshlrev_b32_e32 v200, 16, v36
	v_and_b32_e32 v201, 0xffff0000, v36
	v_lshlrev_b32_e32 v202, 16, v37
	v_and_b32_e32 v203, 0xffff0000, v37
	v_fmac_f32_e32 v196, v90, v188
	v_fmac_f32_e32 v197, v91, v189
	v_fmac_f32_e32 v198, v92, v190
	v_fmac_f32_e32 v199, v93, v191
	v_fmac_f32_e32 v200, v94, v192
	v_fmac_f32_e32 v201, v95, v193
	v_fmac_f32_e32 v202, v96, v194
	v_fmac_f32_e32 v203, v97, v195
	v_cvt_pk_bf16_f32 v34, v196, v197
	v_cvt_pk_bf16_f32 v35, v198, v199
	v_cvt_pk_bf16_f32 v36, v200, v201
	v_cvt_pk_bf16_f32 v37, v202, v203
	global_store_dwordx4 v8, v[34:37], s[6:7]
	s_waitcnt lgkmcnt(0)
	v_lshlrev_b32_e32 v188, 16, v184
	v_and_b32_e32 v189, 0xffff0000, v184
	v_lshlrev_b32_e32 v190, 16, v185
	v_and_b32_e32 v191, 0xffff0000, v185
	v_lshlrev_b32_e32 v192, 16, v186
	v_and_b32_e32 v193, 0xffff0000, v186
	v_lshlrev_b32_e32 v194, 16, v187
	v_and_b32_e32 v195, 0xffff0000, v187
	ds_read_b128 v[172:175], v4 offset:256
	ds_read_b128 v[176:179], v4 offset:17152
	ds_read_b128 v[180:183], v4 offset:34048
	ds_read_b128 v[184:187], v4 offset:50944
	v_lshlrev_b32_e32 v196, 16, v38
	v_and_b32_e32 v197, 0xffff0000, v38
	v_lshlrev_b32_e32 v198, 16, v39
	v_and_b32_e32 v199, 0xffff0000, v39
	v_lshlrev_b32_e32 v200, 16, v40
	v_and_b32_e32 v201, 0xffff0000, v40
	v_lshlrev_b32_e32 v202, 16, v41
	v_and_b32_e32 v203, 0xffff0000, v41
	v_fmac_f32_e32 v196, v90, v188
	v_fmac_f32_e32 v197, v91, v189
	v_fmac_f32_e32 v198, v92, v190
	v_fmac_f32_e32 v199, v93, v191
	v_fmac_f32_e32 v200, v94, v192
	v_fmac_f32_e32 v201, v95, v193
	v_fmac_f32_e32 v202, v96, v194
	v_fmac_f32_e32 v203, v97, v195
	v_cvt_pk_bf16_f32 v38, v196, v197
	v_cvt_pk_bf16_f32 v39, v198, v199
	v_cvt_pk_bf16_f32 v40, v200, v201
	v_cvt_pk_bf16_f32 v41, v202, v203
	global_store_dwordx4 v9, v[38:41], s[6:7]
	s_waitcnt lgkmcnt(3)
	v_lshlrev_b32_e32 v188, 16, v172
	v_and_b32_e32 v189, 0xffff0000, v172
	v_lshlrev_b32_e32 v190, 16, v173
	v_and_b32_e32 v191, 0xffff0000, v173
	v_lshlrev_b32_e32 v192, 16, v174
	v_and_b32_e32 v193, 0xffff0000, v174
	v_lshlrev_b32_e32 v194, 16, v175
	v_and_b32_e32 v195, 0xffff0000, v175
	s_waitcnt vmcnt(16)
	v_lshlrev_b32_e32 v196, 16, v42
	v_and_b32_e32 v197, 0xffff0000, v42
	v_lshlrev_b32_e32 v198, 16, v43
	v_and_b32_e32 v199, 0xffff0000, v43
	v_lshlrev_b32_e32 v200, 16, v44
	v_and_b32_e32 v201, 0xffff0000, v44
	v_lshlrev_b32_e32 v202, 16, v45
	v_and_b32_e32 v203, 0xffff0000, v45
	v_fmac_f32_e32 v196, v98, v188
	v_fmac_f32_e32 v197, v99, v189
	v_fmac_f32_e32 v198, v100, v190
	v_fmac_f32_e32 v199, v101, v191
	v_fmac_f32_e32 v200, v102, v192
	v_fmac_f32_e32 v201, v103, v193
	v_fmac_f32_e32 v202, v104, v194
	v_fmac_f32_e32 v203, v105, v195
	v_cvt_pk_bf16_f32 v42, v196, v197
	v_cvt_pk_bf16_f32 v43, v198, v199
	v_cvt_pk_bf16_f32 v44, v200, v201
	v_cvt_pk_bf16_f32 v45, v202, v203
	global_store_dwordx4 v10, v[42:45], s[6:7]
	s_waitcnt lgkmcnt(2)
	v_lshlrev_b32_e32 v188, 16, v176
	v_and_b32_e32 v189, 0xffff0000, v176
	v_lshlrev_b32_e32 v190, 16, v177
	v_and_b32_e32 v191, 0xffff0000, v177
	v_lshlrev_b32_e32 v192, 16, v178
	v_and_b32_e32 v193, 0xffff0000, v178
	v_lshlrev_b32_e32 v194, 16, v179
	v_and_b32_e32 v195, 0xffff0000, v179
	v_lshlrev_b32_e32 v196, 16, v46
	v_and_b32_e32 v197, 0xffff0000, v46
	v_lshlrev_b32_e32 v198, 16, v47
	v_and_b32_e32 v199, 0xffff0000, v47
	v_lshlrev_b32_e32 v200, 16, v48
	v_and_b32_e32 v201, 0xffff0000, v48
	v_lshlrev_b32_e32 v202, 16, v49
	v_and_b32_e32 v203, 0xffff0000, v49
	v_fmac_f32_e32 v196, v98, v188
	v_fmac_f32_e32 v197, v99, v189
	v_fmac_f32_e32 v198, v100, v190
	v_fmac_f32_e32 v199, v101, v191
	v_fmac_f32_e32 v200, v102, v192
	v_fmac_f32_e32 v201, v103, v193
	v_fmac_f32_e32 v202, v104, v194
	v_fmac_f32_e32 v203, v105, v195
	v_cvt_pk_bf16_f32 v46, v196, v197
	v_cvt_pk_bf16_f32 v47, v198, v199
	v_cvt_pk_bf16_f32 v48, v200, v201
	v_cvt_pk_bf16_f32 v49, v202, v203
	global_store_dwordx4 v11, v[46:49], s[6:7]
	s_waitcnt lgkmcnt(1)
	v_lshlrev_b32_e32 v188, 16, v180
	v_and_b32_e32 v189, 0xffff0000, v180
	v_lshlrev_b32_e32 v190, 16, v181
	v_and_b32_e32 v191, 0xffff0000, v181
	v_lshlrev_b32_e32 v192, 16, v182
	v_and_b32_e32 v193, 0xffff0000, v182
	v_lshlrev_b32_e32 v194, 16, v183
	v_and_b32_e32 v195, 0xffff0000, v183
	v_lshlrev_b32_e32 v196, 16, v50
	v_and_b32_e32 v197, 0xffff0000, v50
	v_lshlrev_b32_e32 v198, 16, v51
	v_and_b32_e32 v199, 0xffff0000, v51
	v_lshlrev_b32_e32 v200, 16, v52
	v_and_b32_e32 v201, 0xffff0000, v52
	v_lshlrev_b32_e32 v202, 16, v53
	v_and_b32_e32 v203, 0xffff0000, v53
	v_fmac_f32_e32 v196, v98, v188
	v_fmac_f32_e32 v197, v99, v189
	v_fmac_f32_e32 v198, v100, v190
	v_fmac_f32_e32 v199, v101, v191
	v_fmac_f32_e32 v200, v102, v192
	v_fmac_f32_e32 v201, v103, v193
	v_fmac_f32_e32 v202, v104, v194
	v_fmac_f32_e32 v203, v105, v195
	v_cvt_pk_bf16_f32 v50, v196, v197
	v_cvt_pk_bf16_f32 v51, v198, v199
	v_cvt_pk_bf16_f32 v52, v200, v201
	v_cvt_pk_bf16_f32 v53, v202, v203
	global_store_dwordx4 v12, v[50:53], s[6:7]
	s_waitcnt lgkmcnt(0)
	v_lshlrev_b32_e32 v188, 16, v184
	v_and_b32_e32 v189, 0xffff0000, v184
	v_lshlrev_b32_e32 v190, 16, v185
	v_and_b32_e32 v191, 0xffff0000, v185
	v_lshlrev_b32_e32 v192, 16, v186
	v_and_b32_e32 v193, 0xffff0000, v186
	v_lshlrev_b32_e32 v194, 16, v187
	v_and_b32_e32 v195, 0xffff0000, v187
	ds_read_b128 v[172:175], v5
	ds_read_b128 v[176:179], v5 offset:16896
	ds_read_b128 v[180:183], v5 offset:33792
	ds_read_b128 v[184:187], v5 offset:50688
	v_lshlrev_b32_e32 v196, 16, v54
	v_and_b32_e32 v197, 0xffff0000, v54
	v_lshlrev_b32_e32 v198, 16, v55
	v_and_b32_e32 v199, 0xffff0000, v55
	v_lshlrev_b32_e32 v200, 16, v56
	v_and_b32_e32 v201, 0xffff0000, v56
	v_lshlrev_b32_e32 v202, 16, v57
	v_and_b32_e32 v203, 0xffff0000, v57
	v_fmac_f32_e32 v196, v98, v188
	v_fmac_f32_e32 v197, v99, v189
	v_fmac_f32_e32 v198, v100, v190
	v_fmac_f32_e32 v199, v101, v191
	v_fmac_f32_e32 v200, v102, v192
	v_fmac_f32_e32 v201, v103, v193
	v_fmac_f32_e32 v202, v104, v194
	v_fmac_f32_e32 v203, v105, v195
	v_cvt_pk_bf16_f32 v54, v196, v197
	v_cvt_pk_bf16_f32 v55, v198, v199
	v_cvt_pk_bf16_f32 v56, v200, v201
	v_cvt_pk_bf16_f32 v57, v202, v203
	global_store_dwordx4 v13, v[54:57], s[6:7]
	s_waitcnt lgkmcnt(3)
	v_lshlrev_b32_e32 v188, 16, v172
	v_and_b32_e32 v189, 0xffff0000, v172
	v_lshlrev_b32_e32 v190, 16, v173
	v_and_b32_e32 v191, 0xffff0000, v173
	v_lshlrev_b32_e32 v192, 16, v174
	v_and_b32_e32 v193, 0xffff0000, v174
	v_lshlrev_b32_e32 v194, 16, v175
	v_and_b32_e32 v195, 0xffff0000, v175
	s_waitcnt vmcnt(14)
	v_lshlrev_b32_e32 v196, 16, v58
	v_and_b32_e32 v197, 0xffff0000, v58
	v_lshlrev_b32_e32 v198, 16, v59
	v_and_b32_e32 v199, 0xffff0000, v59
	v_lshlrev_b32_e32 v200, 16, v60
	v_and_b32_e32 v201, 0xffff0000, v60
	v_lshlrev_b32_e32 v202, 16, v61
	v_and_b32_e32 v203, 0xffff0000, v61
	v_fmac_f32_e32 v196, v106, v188
	v_fmac_f32_e32 v197, v107, v189
	v_fmac_f32_e32 v198, v108, v190
	v_fmac_f32_e32 v199, v109, v191
	v_fmac_f32_e32 v200, v110, v192
	v_fmac_f32_e32 v201, v111, v193
	v_fmac_f32_e32 v202, v112, v194
	v_fmac_f32_e32 v203, v113, v195
	v_cvt_pk_bf16_f32 v58, v196, v197
	v_cvt_pk_bf16_f32 v59, v198, v199
	v_cvt_pk_bf16_f32 v60, v200, v201
	v_cvt_pk_bf16_f32 v61, v202, v203
	global_store_dwordx4 v14, v[58:61], s[6:7]
	s_waitcnt lgkmcnt(2)
	v_lshlrev_b32_e32 v188, 16, v176
	v_and_b32_e32 v189, 0xffff0000, v176
	v_lshlrev_b32_e32 v190, 16, v177
	v_and_b32_e32 v191, 0xffff0000, v177
	v_lshlrev_b32_e32 v192, 16, v178
	v_and_b32_e32 v193, 0xffff0000, v178
	v_lshlrev_b32_e32 v194, 16, v179
	v_and_b32_e32 v195, 0xffff0000, v179
	v_lshlrev_b32_e32 v196, 16, v62
	v_and_b32_e32 v197, 0xffff0000, v62
	v_lshlrev_b32_e32 v198, 16, v63
	v_and_b32_e32 v199, 0xffff0000, v63
	v_lshlrev_b32_e32 v200, 16, v64
	v_and_b32_e32 v201, 0xffff0000, v64
	v_lshlrev_b32_e32 v202, 16, v65
	v_and_b32_e32 v203, 0xffff0000, v65
	v_fmac_f32_e32 v196, v106, v188
	v_fmac_f32_e32 v197, v107, v189
	v_fmac_f32_e32 v198, v108, v190
	v_fmac_f32_e32 v199, v109, v191
	v_fmac_f32_e32 v200, v110, v192
	v_fmac_f32_e32 v201, v111, v193
	v_fmac_f32_e32 v202, v112, v194
	v_fmac_f32_e32 v203, v113, v195
	v_cvt_pk_bf16_f32 v62, v196, v197
	v_cvt_pk_bf16_f32 v63, v198, v199
	v_cvt_pk_bf16_f32 v64, v200, v201
	v_cvt_pk_bf16_f32 v65, v202, v203
	global_store_dwordx4 v15, v[62:65], s[6:7]
	s_waitcnt lgkmcnt(1)
	v_lshlrev_b32_e32 v188, 16, v180
	v_and_b32_e32 v189, 0xffff0000, v180
	v_lshlrev_b32_e32 v190, 16, v181
	v_and_b32_e32 v191, 0xffff0000, v181
	v_lshlrev_b32_e32 v192, 16, v182
	v_and_b32_e32 v193, 0xffff0000, v182
	v_lshlrev_b32_e32 v194, 16, v183
	v_and_b32_e32 v195, 0xffff0000, v183
	v_lshlrev_b32_e32 v196, 16, v66
	v_and_b32_e32 v197, 0xffff0000, v66
	v_lshlrev_b32_e32 v198, 16, v67
	v_and_b32_e32 v199, 0xffff0000, v67
	v_lshlrev_b32_e32 v200, 16, v68
	v_and_b32_e32 v201, 0xffff0000, v68
	v_lshlrev_b32_e32 v202, 16, v69
	v_and_b32_e32 v203, 0xffff0000, v69
	v_fmac_f32_e32 v196, v106, v188
	v_fmac_f32_e32 v197, v107, v189
	v_fmac_f32_e32 v198, v108, v190
	v_fmac_f32_e32 v199, v109, v191
	v_fmac_f32_e32 v200, v110, v192
	v_fmac_f32_e32 v201, v111, v193
	v_fmac_f32_e32 v202, v112, v194
	v_fmac_f32_e32 v203, v113, v195
	v_cvt_pk_bf16_f32 v66, v196, v197
	v_cvt_pk_bf16_f32 v67, v198, v199
	v_cvt_pk_bf16_f32 v68, v200, v201
	v_cvt_pk_bf16_f32 v69, v202, v203
	global_store_dwordx4 v16, v[66:69], s[6:7]
	s_waitcnt lgkmcnt(0)
	v_lshlrev_b32_e32 v188, 16, v184
	v_and_b32_e32 v189, 0xffff0000, v184
	v_lshlrev_b32_e32 v190, 16, v185
	v_and_b32_e32 v191, 0xffff0000, v185
	v_lshlrev_b32_e32 v192, 16, v186
	v_and_b32_e32 v193, 0xffff0000, v186
	v_lshlrev_b32_e32 v194, 16, v187
	v_and_b32_e32 v195, 0xffff0000, v187
	ds_read_b128 v[172:175], v5 offset:256
	ds_read_b128 v[176:179], v5 offset:17152
	ds_read_b128 v[180:183], v5 offset:34048
	ds_read_b128 v[184:187], v5 offset:50944
	v_lshlrev_b32_e32 v196, 16, v70
	v_and_b32_e32 v197, 0xffff0000, v70
	v_lshlrev_b32_e32 v198, 16, v71
	v_and_b32_e32 v199, 0xffff0000, v71
	v_lshlrev_b32_e32 v200, 16, v72
	v_and_b32_e32 v201, 0xffff0000, v72
	v_lshlrev_b32_e32 v202, 16, v73
	v_and_b32_e32 v203, 0xffff0000, v73
	v_fmac_f32_e32 v196, v106, v188
	v_fmac_f32_e32 v197, v107, v189
	v_fmac_f32_e32 v198, v108, v190
	v_fmac_f32_e32 v199, v109, v191
	v_fmac_f32_e32 v200, v110, v192
	v_fmac_f32_e32 v201, v111, v193
	v_fmac_f32_e32 v202, v112, v194
	v_fmac_f32_e32 v203, v113, v195
	v_cvt_pk_bf16_f32 v70, v196, v197
	v_cvt_pk_bf16_f32 v71, v198, v199
	v_cvt_pk_bf16_f32 v72, v200, v201
	v_cvt_pk_bf16_f32 v73, v202, v203
	global_store_dwordx4 v17, v[70:73], s[6:7]
	s_waitcnt lgkmcnt(3)
	v_lshlrev_b32_e32 v188, 16, v172
	v_and_b32_e32 v189, 0xffff0000, v172
	v_lshlrev_b32_e32 v190, 16, v173
	v_and_b32_e32 v191, 0xffff0000, v173
	v_lshlrev_b32_e32 v192, 16, v174
	v_and_b32_e32 v193, 0xffff0000, v174
	v_lshlrev_b32_e32 v194, 16, v175
	v_and_b32_e32 v195, 0xffff0000, v175
	s_waitcnt vmcnt(12)
	v_lshlrev_b32_e32 v196, 16, v74
	v_and_b32_e32 v197, 0xffff0000, v74
	v_lshlrev_b32_e32 v198, 16, v75
	v_and_b32_e32 v199, 0xffff0000, v75
	v_lshlrev_b32_e32 v200, 16, v76
	v_and_b32_e32 v201, 0xffff0000, v76
	v_lshlrev_b32_e32 v202, 16, v77
	v_and_b32_e32 v203, 0xffff0000, v77
	v_fmac_f32_e32 v196, v114, v188
	v_fmac_f32_e32 v197, v115, v189
	v_fmac_f32_e32 v198, v116, v190
	v_fmac_f32_e32 v199, v117, v191
	v_fmac_f32_e32 v200, v118, v192
	v_fmac_f32_e32 v201, v119, v193
	v_fmac_f32_e32 v202, v120, v194
	v_fmac_f32_e32 v203, v121, v195
	v_cvt_pk_bf16_f32 v74, v196, v197
	v_cvt_pk_bf16_f32 v75, v198, v199
	v_cvt_pk_bf16_f32 v76, v200, v201
	v_cvt_pk_bf16_f32 v77, v202, v203
	global_store_dwordx4 v18, v[74:77], s[6:7]
	s_waitcnt lgkmcnt(2)
	v_lshlrev_b32_e32 v188, 16, v176
	v_and_b32_e32 v189, 0xffff0000, v176
	v_lshlrev_b32_e32 v190, 16, v177
	v_and_b32_e32 v191, 0xffff0000, v177
	v_lshlrev_b32_e32 v192, 16, v178
	v_and_b32_e32 v193, 0xffff0000, v178
	v_lshlrev_b32_e32 v194, 16, v179
	v_and_b32_e32 v195, 0xffff0000, v179
	v_lshlrev_b32_e32 v196, 16, v78
	v_and_b32_e32 v197, 0xffff0000, v78
	v_lshlrev_b32_e32 v198, 16, v79
	v_and_b32_e32 v199, 0xffff0000, v79
	v_lshlrev_b32_e32 v200, 16, v80
	v_and_b32_e32 v201, 0xffff0000, v80
	v_lshlrev_b32_e32 v202, 16, v81
	v_and_b32_e32 v203, 0xffff0000, v81
	v_fmac_f32_e32 v196, v114, v188
	v_fmac_f32_e32 v197, v115, v189
	v_fmac_f32_e32 v198, v116, v190
	v_fmac_f32_e32 v199, v117, v191
	v_fmac_f32_e32 v200, v118, v192
	v_fmac_f32_e32 v201, v119, v193
	v_fmac_f32_e32 v202, v120, v194
	v_fmac_f32_e32 v203, v121, v195
	v_cvt_pk_bf16_f32 v78, v196, v197
	v_cvt_pk_bf16_f32 v79, v198, v199
	v_cvt_pk_bf16_f32 v80, v200, v201
	v_cvt_pk_bf16_f32 v81, v202, v203
	global_store_dwordx4 v19, v[78:81], s[6:7]
	s_waitcnt lgkmcnt(1)
	v_lshlrev_b32_e32 v188, 16, v180
	v_and_b32_e32 v189, 0xffff0000, v180
	v_lshlrev_b32_e32 v190, 16, v181
	v_and_b32_e32 v191, 0xffff0000, v181
	v_lshlrev_b32_e32 v192, 16, v182
	v_and_b32_e32 v193, 0xffff0000, v182
	v_lshlrev_b32_e32 v194, 16, v183
	v_and_b32_e32 v195, 0xffff0000, v183
	v_lshlrev_b32_e32 v196, 16, v82
	v_and_b32_e32 v197, 0xffff0000, v82
	v_lshlrev_b32_e32 v198, 16, v83
	v_and_b32_e32 v199, 0xffff0000, v83
	v_lshlrev_b32_e32 v200, 16, v84
	v_and_b32_e32 v201, 0xffff0000, v84
	v_lshlrev_b32_e32 v202, 16, v85
	v_and_b32_e32 v203, 0xffff0000, v85
	v_fmac_f32_e32 v196, v114, v188
	v_fmac_f32_e32 v197, v115, v189
	v_fmac_f32_e32 v198, v116, v190
	v_fmac_f32_e32 v199, v117, v191
	v_fmac_f32_e32 v200, v118, v192
	v_fmac_f32_e32 v201, v119, v193
	v_fmac_f32_e32 v202, v120, v194
	v_fmac_f32_e32 v203, v121, v195
	v_cvt_pk_bf16_f32 v82, v196, v197
	v_cvt_pk_bf16_f32 v83, v198, v199
	v_cvt_pk_bf16_f32 v84, v200, v201
	v_cvt_pk_bf16_f32 v85, v202, v203
	global_store_dwordx4 v20, v[82:85], s[6:7]
	s_waitcnt lgkmcnt(0)
	v_lshlrev_b32_e32 v188, 16, v184
	v_and_b32_e32 v189, 0xffff0000, v184
	v_lshlrev_b32_e32 v190, 16, v185
	v_and_b32_e32 v191, 0xffff0000, v185
	v_lshlrev_b32_e32 v192, 16, v186
	v_and_b32_e32 v193, 0xffff0000, v186
	v_lshlrev_b32_e32 v194, 16, v187
	v_and_b32_e32 v195, 0xffff0000, v187
	v_lshlrev_b32_e32 v196, 16, v86
	v_and_b32_e32 v197, 0xffff0000, v86
	v_lshlrev_b32_e32 v198, 16, v87
	v_and_b32_e32 v199, 0xffff0000, v87
	v_lshlrev_b32_e32 v200, 16, v88
	v_and_b32_e32 v201, 0xffff0000, v88
	v_lshlrev_b32_e32 v202, 16, v89
	v_and_b32_e32 v203, 0xffff0000, v89
	v_fmac_f32_e32 v196, v114, v188
	v_fmac_f32_e32 v197, v115, v189
	v_fmac_f32_e32 v198, v116, v190
	v_fmac_f32_e32 v199, v117, v191
	v_fmac_f32_e32 v200, v118, v192
	v_fmac_f32_e32 v201, v119, v193
	v_fmac_f32_e32 v202, v120, v194
	v_fmac_f32_e32 v203, v121, v195
	v_cvt_pk_bf16_f32 v86, v196, v197
	v_cvt_pk_bf16_f32 v87, v198, v199
	v_cvt_pk_bf16_f32 v88, v200, v201
	v_cvt_pk_bf16_f32 v89, v202, v203
	global_store_dwordx4 v21, v[86:89], s[6:7]
	s_mov_b64 s[4:5], 0
	s_barrier
	s_branch .LBB0_1883

	.amdhsa_kernel _Z11mega_kernel6Params
		.amdhsa_group_segment_fixed_size 0
		.amdhsa_private_segment_fixed_size 0
		.amdhsa_kernarg_size 504
		.amdhsa_user_sgpr_count 2
		.amdhsa_user_sgpr_dispatch_ptr 0
		.amdhsa_user_sgpr_queue_ptr 0
		.amdhsa_user_sgpr_kernarg_segment_ptr 1
		.amdhsa_user_sgpr_dispatch_id 0
		.amdhsa_user_sgpr_kernarg_preload_length 0
		.amdhsa_user_sgpr_kernarg_preload_offset 0
		.amdhsa_user_sgpr_private_segment_size 0
		.amdhsa_uses_dynamic_stack 0
		.amdhsa_enable_private_segment 0
		.amdhsa_system_sgpr_workgroup_id_x 1
		.amdhsa_system_sgpr_workgroup_id_y 0
		.amdhsa_system_sgpr_workgroup_id_z 0
		.amdhsa_system_sgpr_workgroup_info 0
		.amdhsa_system_vgpr_workitem_id 0
		.amdhsa_next_free_vgpr 255
		.amdhsa_next_free_sgpr 102
		.amdhsa_accum_offset 256
		.amdhsa_reserve_vcc 1
		.amdhsa_float_round_mode_32 0
		.amdhsa_float_round_mode_16_64 0
		.amdhsa_float_denorm_mode_32 3
		.amdhsa_float_denorm_mode_16_64 3
		.amdhsa_dx10_clamp 1
		.amdhsa_ieee_mode 1
		.amdhsa_fp16_overflow 0
		.amdhsa_tg_split 0
		.amdhsa_exception_fp_ieee_invalid_op 0
		.amdhsa_exception_fp_denorm_src 0
		.amdhsa_exception_fp_ieee_div_zero 0
		.amdhsa_exception_fp_ieee_overflow 0
		.amdhsa_exception_fp_ieee_underflow 0
		.amdhsa_exception_fp_ieee_inexact 0
		.amdhsa_exception_int_div_zero 0
	.end_amdhsa_kernel

amdhsa.kernels:
  - .agpr_count:     0
    .args:
      - .offset:         0
        .size:           248
        .value_kind:     by_value
      - .offset:         248
        .size:           4
        .value_kind:     hidden_block_count_x
      - .offset:         252
        .size:           4
        .value_kind:     hidden_block_count_y
      - .offset:         256
        .size:           4
        .value_kind:     hidden_block_count_z
      - .offset:         260
        .size:           2
        .value_kind:     hidden_group_size_x
      - .offset:         262
        .size:           2
        .value_kind:     hidden_group_size_y
      - .offset:         264
        .size:           2
        .value_kind:     hidden_group_size_z
      - .offset:         266
        .size:           2
        .value_kind:     hidden_remainder_x
      - .offset:         268
        .size:           2
        .value_kind:     hidden_remainder_y
      - .offset:         270
        .size:           2
        .value_kind:     hidden_remainder_z
      - .offset:         288
        .size:           8
        .value_kind:     hidden_global_offset_x
      - .offset:         296
        .size:           8
        .value_kind:     hidden_global_offset_y
      - .offset:         304
        .size:           8
        .value_kind:     hidden_global_offset_z
      - .offset:         312
        .size:           2
        .value_kind:     hidden_grid_dims
      - .offset:         368
        .size:           4
        .value_kind:     hidden_dynamic_lds_size
    .group_segment_fixed_size: 0
    .kernarg_segment_align: 8
    .kernarg_segment_size: 504
    .language:       OpenCL C
    .language_version:
      - 2
      - 0
    .max_flat_workgroup_size: 512
    .name:           _Z11mega_kernel6Params
    .private_segment_fixed_size: 0
    .sgpr_count:     108
    .sgpr_spill_count: 54
    .symbol:         _Z11mega_kernel6Params.kd
    .uniform_work_group_size: 1
    .uses_dynamic_stack: false
    .vgpr_count:     255
    .vgpr_spill_count: 0
    .wavefront_size: 64
